# EpiResid bf16 GEMM epilogues (P8,P13,P16): all 16 base-row loads hoisted to epilogue start into fresh VGPRs, one wait instead of per-group vmcnt ladder; nfv 256
# speedup vs baseline: 1.0040x; 1.0024x over previous
.LBB0_712:
	v_lshl_add_u32 v150, s53, 8, v152
	v_ashrrev_i32_e32 v151, 31, v150
	v_lshl_or_b32 v148, s10, 8, v154
	v_lshlrev_b64 v[160:161], 11, v[150:151]
	v_ashrrev_i32_e32 v149, 31, v148
	v_lshl_add_u64 v[160:161], s[14:15], 0, v[160:161]
	v_lshl_add_u64 v[170:171], v[148:149], 1, v[160:161]
	global_load_dwordx4 v[162:165], v[170:171], off
	global_load_dwordx4 v[166:169], v[170:171], off offset:256
	s_mov_b64 s[100:101], 0x8000
	v_lshl_add_u64 v[232:233], v[170:171], 0, s[100:101]
	global_load_dwordx4 v[184:187], v[232:233], off
	global_load_dwordx4 v[188:191], v[232:233], off offset:256
	s_mov_b64 s[100:101], 0x10000
	v_lshl_add_u64 v[232:233], v[170:171], 0, s[100:101]
	global_load_dwordx4 v[192:195], v[232:233], off
	global_load_dwordx4 v[196:199], v[232:233], off offset:256
	s_mov_b64 s[100:101], 0x18000
	v_lshl_add_u64 v[232:233], v[170:171], 0, s[100:101]
	global_load_dwordx4 v[200:203], v[232:233], off
	global_load_dwordx4 v[204:207], v[232:233], off offset:256
	s_mov_b64 s[100:101], 0x40000
	v_lshl_add_u64 v[232:233], v[170:171], 0, s[100:101]
	global_load_dwordx4 v[208:211], v[232:233], off
	global_load_dwordx4 v[212:215], v[232:233], off offset:256
	s_mov_b64 s[100:101], 0x48000
	v_lshl_add_u64 v[232:233], v[170:171], 0, s[100:101]
	global_load_dwordx4 v[216:219], v[232:233], off
	global_load_dwordx4 v[220:223], v[232:233], off offset:256
	s_mov_b64 s[100:101], 0x50000
	v_lshl_add_u64 v[232:233], v[170:171], 0, s[100:101]
	global_load_dwordx4 v[224:227], v[232:233], off
	global_load_dwordx4 v[228:231], v[232:233], off offset:256
	s_mov_b64 s[100:101], 0x58000
	v_lshl_add_u64 v[232:233], v[170:171], 0, s[100:101]
	global_load_dwordx4 v[238:241], v[232:233], off
	global_load_dwordx4 v[242:245], v[232:233], off offset:256
	v_and_b32_e32 v161, 64, v159
	v_xor_b32_e32 v160, 16, v159
	v_add_u32_e32 v161, 64, v161
	v_xor_b32_e32 v172, 32, v159
	v_cmp_lt_i32_e32 vcc, v160, v161
	s_lshl_b32 s24, s10, 2
	s_ashr_i32 s25, s24, 31
	v_cndmask_b32_e32 v160, v159, v160, vcc
	v_cmp_lt_i32_e32 vcc, v172, v161
	v_lshlrev_b32_e32 v161, 2, v160
	s_waitcnt vmcnt(0)
	v_and_b32_e32 v173, 0xffff0000, v162
	v_cndmask_b32_e32 v172, v159, v172, vcc
	v_lshlrev_b32_e32 v160, 2, v172
	v_lshlrev_b32_e32 v172, 16, v162
	v_lshlrev_b32_e32 v162, 16, v163
	v_and_b32_e32 v163, 0xffff0000, v163
	v_lshlrev_b32_e32 v174, 16, v164
	v_and_b32_e32 v175, 0xffff0000, v164
	v_lshlrev_b32_e32 v164, 16, v165
	v_and_b32_e32 v165, 0xffff0000, v165
	v_lshlrev_b32_e32 v176, 16, v166
	v_and_b32_e32 v177, 0xffff0000, v166
	v_lshlrev_b32_e32 v166, 16, v167
	v_and_b32_e32 v167, 0xffff0000, v167
	v_lshlrev_b32_e32 v178, 16, v168
	v_and_b32_e32 v179, 0xffff0000, v168
	v_lshlrev_b32_e32 v168, 16, v169
	v_and_b32_e32 v169, 0xffff0000, v169
	v_pk_add_f32 v[124:125], v[124:125], v[172:173]
	v_pk_add_f32 v[126:127], v[126:127], v[162:163]
	v_pk_add_f32 v[120:121], v[120:121], v[174:175]
	v_pk_add_f32 v[122:123], v[122:123], v[164:165]
	v_pk_add_f32 v[116:117], v[116:117], v[176:177]
	v_pk_add_f32 v[118:119], v[118:119], v[166:167]
	v_pk_add_f32 v[162:163], v[112:113], v[178:179]
	v_pk_add_f32 v[164:165], v[114:115], v[168:169]
	v_cvt_pk_bf16_f32 v112, v124, v125
	v_cvt_pk_bf16_f32 v113, v126, v127
	v_pk_mul_f32 v[114:115], v[124:125], v[124:125]
	v_pk_mul_f32 v[124:125], v[126:127], v[126:127]
	v_pk_mul_f32 v[126:127], v[120:121], v[120:121]
	v_pk_mul_f32 v[166:167], v[122:123], v[122:123]
	v_pk_mul_f32 v[168:169], v[116:117], v[116:117]
	v_pk_mul_f32 v[172:173], v[118:119], v[118:119]
	v_pk_mul_f32 v[174:175], v[162:163], v[162:163]
	v_pk_mul_f32 v[176:177], v[164:165], v[164:165]
	v_add_f32_e32 v174, v174, v175
	v_add_f32_e32 v176, v176, v177
	v_add_f32_e32 v172, v172, v173
	v_add_f32_e32 v168, v168, v169
	v_add_f32_e32 v166, v166, v167
	v_add_f32_e32 v126, v126, v127
	v_add_f32_e32 v124, v124, v125
	v_add_f32_e32 v114, v114, v115
	v_add_f32_e32 v115, v174, v176
	v_add_f32_e32 v125, v168, v172
	v_add_f32_e32 v126, v126, v166
	v_add_f32_e32 v114, v114, v124
	v_add_f32_e32 v115, v125, v115
	v_add_f32_e32 v114, v114, v126
	v_add_f32_e32 v124, v114, v115
	ds_bpermute_b32 v125, v161, v124
	v_cvt_pk_bf16_f32 v114, v120, v121
	v_cvt_pk_bf16_f32 v115, v122, v123
	global_store_dwordx4 v[170:171], v[112:115], off
	s_waitcnt lgkmcnt(0)
	s_nop 0
	v_add_f32_e32 v112, v124, v125
	ds_bpermute_b32 v113, v160, v112
	v_cvt_pk_bf16_f32 v114, v116, v117
	v_cvt_pk_bf16_f32 v115, v118, v119
	v_cvt_pk_bf16_f32 v116, v162, v163
	v_cvt_pk_bf16_f32 v117, v164, v165
	global_store_dwordx4 v[170:171], v[114:117], off offset:256
	s_and_saveexec_b64 s[26:27], s[4:5]
	s_cbranch_execz .LBB0_714
	v_lshlrev_b64 v[114:115], 6, v[150:151]
	v_lshl_add_u64 v[114:115], s[16:17], 0, v[114:115]
	v_lshl_add_u64 v[114:115], s[24:25], 2, v[114:115]
	s_lshl_b32 s10, s40, 2
	v_lshl_add_u64 v[114:115], v[114:115], 0, s[10:11]
	s_waitcnt lgkmcnt(0)
	v_add_f32_e32 v112, v112, v113
	global_store_dword v[114:115], v112, off
.LBB0_714:
	s_or_b64 exec, exec, s[26:27]
	v_or_b32_e32 v112, 16, v150
	s_waitcnt lgkmcnt(0)
	v_ashrrev_i32_e32 v113, 31, v112
	v_lshlrev_b64 v[114:115], 11, v[112:113]
	v_lshl_add_u64 v[114:115], s[14:15], 0, v[114:115]
	v_lshl_add_u64 v[122:123], v[148:149], 1, v[114:115]
	s_nop 1
	v_mov_b32_e32 v114, v184
	v_mov_b32_e32 v115, v185
	v_mov_b32_e32 v116, v186
	v_mov_b32_e32 v117, v187
	v_mov_b32_e32 v118, v188
	v_mov_b32_e32 v119, v189
	v_mov_b32_e32 v120, v190
	v_mov_b32_e32 v121, v191
	v_lshlrev_b32_e32 v124, 16, v114
	v_and_b32_e32 v125, 0xffff0000, v114
	v_lshlrev_b32_e32 v114, 16, v115
	v_and_b32_e32 v115, 0xffff0000, v115
	v_lshlrev_b32_e32 v126, 16, v116
	v_and_b32_e32 v127, 0xffff0000, v116
	v_lshlrev_b32_e32 v116, 16, v117
	v_and_b32_e32 v117, 0xffff0000, v117
	v_lshlrev_b32_e32 v162, 16, v118
	v_and_b32_e32 v163, 0xffff0000, v118
	v_lshlrev_b32_e32 v118, 16, v119
	v_and_b32_e32 v119, 0xffff0000, v119
	v_lshlrev_b32_e32 v164, 16, v120
	v_and_b32_e32 v165, 0xffff0000, v120
	v_lshlrev_b32_e32 v120, 16, v121
	v_and_b32_e32 v121, 0xffff0000, v121
	v_pk_add_f32 v[108:109], v[108:109], v[124:125]
	v_pk_add_f32 v[110:111], v[110:111], v[114:115]
	v_pk_add_f32 v[104:105], v[104:105], v[126:127]
	v_pk_add_f32 v[106:107], v[106:107], v[116:117]
	v_pk_add_f32 v[100:101], v[100:101], v[162:163]
	v_pk_add_f32 v[102:103], v[102:103], v[118:119]
	v_pk_add_f32 v[114:115], v[96:97], v[164:165]
	v_pk_add_f32 v[116:117], v[98:99], v[120:121]
	v_cvt_pk_bf16_f32 v96, v108, v109
	v_cvt_pk_bf16_f32 v97, v110, v111
	v_pk_mul_f32 v[98:99], v[108:109], v[108:109]
	v_pk_mul_f32 v[108:109], v[110:111], v[110:111]
	v_pk_mul_f32 v[110:111], v[104:105], v[104:105]
	v_pk_mul_f32 v[118:119], v[106:107], v[106:107]
	v_pk_mul_f32 v[120:121], v[100:101], v[100:101]
	v_pk_mul_f32 v[124:125], v[102:103], v[102:103]
	v_pk_mul_f32 v[126:127], v[114:115], v[114:115]
	v_pk_mul_f32 v[162:163], v[116:117], v[116:117]
	v_add_f32_e32 v126, v126, v127
	v_add_f32_e32 v151, v162, v163
	v_add_f32_e32 v124, v124, v125
	v_add_f32_e32 v120, v120, v121
	v_add_f32_e32 v118, v118, v119
	v_add_f32_e32 v110, v110, v111
	v_add_f32_e32 v108, v108, v109
	v_add_f32_e32 v98, v98, v99
	v_add_f32_e32 v99, v126, v151
	v_add_f32_e32 v109, v120, v124
	v_add_f32_e32 v110, v110, v118
	v_add_f32_e32 v98, v98, v108
	v_add_f32_e32 v99, v109, v99
	v_add_f32_e32 v98, v98, v110
	v_add_f32_e32 v108, v98, v99
	ds_bpermute_b32 v109, v161, v108
	v_cvt_pk_bf16_f32 v98, v104, v105
	v_cvt_pk_bf16_f32 v99, v106, v107
	global_store_dwordx4 v[122:123], v[96:99], off
	s_waitcnt lgkmcnt(0)
	s_nop 0
	v_add_f32_e32 v96, v108, v109
	ds_bpermute_b32 v97, v160, v96
	v_cvt_pk_bf16_f32 v98, v100, v101
	v_cvt_pk_bf16_f32 v99, v102, v103
	v_cvt_pk_bf16_f32 v100, v114, v115
	v_cvt_pk_bf16_f32 v101, v116, v117
	global_store_dwordx4 v[122:123], v[98:101], off offset:256
	s_and_saveexec_b64 s[26:27], s[4:5]
	s_cbranch_execz .LBB0_716
	v_lshlrev_b64 v[98:99], 6, v[112:113]
	v_lshl_add_u64 v[98:99], s[16:17], 0, v[98:99]
	v_lshl_add_u64 v[98:99], s[24:25], 2, v[98:99]
	s_lshl_b32 s10, s40, 2
	v_lshl_add_u64 v[98:99], v[98:99], 0, s[10:11]
	s_waitcnt lgkmcnt(0)
	v_add_f32_e32 v96, v96, v97
	global_store_dword v[98:99], v96, off
.LBB0_716:
	s_or_b64 exec, exec, s[26:27]
	v_or_b32_e32 v96, 32, v150
	s_waitcnt lgkmcnt(0)
	v_ashrrev_i32_e32 v97, 31, v96
	v_lshlrev_b64 v[98:99], 11, v[96:97]
	v_lshl_add_u64 v[98:99], s[14:15], 0, v[98:99]
	v_lshl_add_u64 v[106:107], v[148:149], 1, v[98:99]
	s_nop 1
	v_mov_b32_e32 v98, v192
	v_mov_b32_e32 v99, v193
	v_mov_b32_e32 v100, v194
	v_mov_b32_e32 v101, v195
	v_mov_b32_e32 v102, v196
	v_mov_b32_e32 v103, v197
	v_mov_b32_e32 v104, v198
	v_mov_b32_e32 v105, v199
	v_lshlrev_b32_e32 v108, 16, v98
	v_and_b32_e32 v109, 0xffff0000, v98
	v_lshlrev_b32_e32 v98, 16, v99
	v_and_b32_e32 v99, 0xffff0000, v99
	v_lshlrev_b32_e32 v110, 16, v100
	v_and_b32_e32 v111, 0xffff0000, v100
	v_lshlrev_b32_e32 v100, 16, v101
	v_and_b32_e32 v101, 0xffff0000, v101
	v_lshlrev_b32_e32 v112, 16, v102
	v_and_b32_e32 v113, 0xffff0000, v102
	v_lshlrev_b32_e32 v102, 16, v103
	v_and_b32_e32 v103, 0xffff0000, v103
	v_lshlrev_b32_e32 v114, 16, v104
	v_and_b32_e32 v115, 0xffff0000, v104
	v_lshlrev_b32_e32 v104, 16, v105
	v_and_b32_e32 v105, 0xffff0000, v105
	v_pk_add_f32 v[92:93], v[92:93], v[108:109]
	v_pk_add_f32 v[94:95], v[94:95], v[98:99]
	v_pk_add_f32 v[88:89], v[88:89], v[110:111]
	v_pk_add_f32 v[90:91], v[90:91], v[100:101]
	v_pk_add_f32 v[84:85], v[84:85], v[112:113]
	v_pk_add_f32 v[86:87], v[86:87], v[102:103]
	v_pk_add_f32 v[98:99], v[80:81], v[114:115]
	v_pk_add_f32 v[100:101], v[82:83], v[104:105]
	v_cvt_pk_bf16_f32 v80, v92, v93
	v_cvt_pk_bf16_f32 v81, v94, v95
	v_pk_mul_f32 v[82:83], v[92:93], v[92:93]
	v_pk_mul_f32 v[92:93], v[94:95], v[94:95]
	v_pk_mul_f32 v[94:95], v[88:89], v[88:89]
	v_pk_mul_f32 v[102:103], v[90:91], v[90:91]
	v_pk_mul_f32 v[104:105], v[84:85], v[84:85]
	v_pk_mul_f32 v[108:109], v[86:87], v[86:87]
	v_pk_mul_f32 v[110:111], v[98:99], v[98:99]
	v_pk_mul_f32 v[112:113], v[100:101], v[100:101]
	v_add_f32_e32 v110, v110, v111
	v_add_f32_e32 v112, v112, v113
	v_add_f32_e32 v108, v108, v109
	v_add_f32_e32 v104, v104, v105
	v_add_f32_e32 v102, v102, v103
	v_add_f32_e32 v94, v94, v95
	v_add_f32_e32 v92, v92, v93
	v_add_f32_e32 v82, v82, v83
	v_add_f32_e32 v83, v110, v112
	v_add_f32_e32 v93, v104, v108
	v_add_f32_e32 v94, v94, v102
	v_add_f32_e32 v82, v82, v92
	v_add_f32_e32 v83, v93, v83
	v_add_f32_e32 v82, v82, v94
	v_add_f32_e32 v92, v82, v83
	ds_bpermute_b32 v93, v161, v92
	v_cvt_pk_bf16_f32 v82, v88, v89
	v_cvt_pk_bf16_f32 v83, v90, v91
	global_store_dwordx4 v[106:107], v[80:83], off
	s_waitcnt lgkmcnt(0)
	s_nop 0
	v_add_f32_e32 v80, v92, v93
	ds_bpermute_b32 v81, v160, v80
	v_cvt_pk_bf16_f32 v82, v84, v85
	v_cvt_pk_bf16_f32 v83, v86, v87
	v_cvt_pk_bf16_f32 v84, v98, v99
	v_cvt_pk_bf16_f32 v85, v100, v101
	global_store_dwordx4 v[106:107], v[82:85], off offset:256
	s_and_saveexec_b64 s[26:27], s[4:5]
	s_cbranch_execz .LBB0_718
	v_lshlrev_b64 v[82:83], 6, v[96:97]
	v_lshl_add_u64 v[82:83], s[16:17], 0, v[82:83]
	v_lshl_add_u64 v[82:83], s[24:25], 2, v[82:83]
	s_lshl_b32 s10, s40, 2
	v_lshl_add_u64 v[82:83], v[82:83], 0, s[10:11]
	s_waitcnt lgkmcnt(0)
	v_add_f32_e32 v80, v80, v81
	global_store_dword v[82:83], v80, off
.LBB0_718:
	s_or_b64 exec, exec, s[26:27]
	v_or_b32_e32 v80, 48, v150
	s_waitcnt lgkmcnt(0)
	v_ashrrev_i32_e32 v81, 31, v80
	v_lshlrev_b64 v[82:83], 11, v[80:81]
	v_lshl_add_u64 v[82:83], s[14:15], 0, v[82:83]
	v_lshl_add_u64 v[90:91], v[148:149], 1, v[82:83]
	s_nop 1
	v_mov_b32_e32 v82, v200
	v_mov_b32_e32 v83, v201
	v_mov_b32_e32 v84, v202
	v_mov_b32_e32 v85, v203
	v_mov_b32_e32 v86, v204
	v_mov_b32_e32 v87, v205
	v_mov_b32_e32 v88, v206
	v_mov_b32_e32 v89, v207
	v_lshlrev_b32_e32 v92, 16, v82
	v_and_b32_e32 v93, 0xffff0000, v82
	v_lshlrev_b32_e32 v82, 16, v83
	v_and_b32_e32 v83, 0xffff0000, v83
	v_lshlrev_b32_e32 v94, 16, v84
	v_and_b32_e32 v95, 0xffff0000, v84
	v_lshlrev_b32_e32 v84, 16, v85
	v_and_b32_e32 v85, 0xffff0000, v85
	v_lshlrev_b32_e32 v96, 16, v86
	v_and_b32_e32 v97, 0xffff0000, v86
	v_lshlrev_b32_e32 v86, 16, v87
	v_and_b32_e32 v87, 0xffff0000, v87
	v_lshlrev_b32_e32 v98, 16, v88
	v_and_b32_e32 v99, 0xffff0000, v88
	v_lshlrev_b32_e32 v88, 16, v89
	v_and_b32_e32 v89, 0xffff0000, v89
	v_pk_add_f32 v[76:77], v[76:77], v[92:93]
	v_pk_add_f32 v[78:79], v[78:79], v[82:83]
	v_pk_add_f32 v[72:73], v[72:73], v[94:95]
	v_pk_add_f32 v[74:75], v[74:75], v[84:85]
	v_pk_add_f32 v[68:69], v[68:69], v[96:97]
	v_pk_add_f32 v[70:71], v[70:71], v[86:87]
	v_pk_add_f32 v[82:83], v[64:65], v[98:99]
	v_pk_add_f32 v[84:85], v[66:67], v[88:89]
	v_cvt_pk_bf16_f32 v64, v76, v77
	v_cvt_pk_bf16_f32 v65, v78, v79
	v_pk_mul_f32 v[66:67], v[76:77], v[76:77]
	v_pk_mul_f32 v[76:77], v[78:79], v[78:79]
	v_pk_mul_f32 v[78:79], v[72:73], v[72:73]
	v_pk_mul_f32 v[86:87], v[74:75], v[74:75]
	v_pk_mul_f32 v[88:89], v[68:69], v[68:69]
	v_pk_mul_f32 v[92:93], v[70:71], v[70:71]
	v_pk_mul_f32 v[94:95], v[82:83], v[82:83]
	v_pk_mul_f32 v[96:97], v[84:85], v[84:85]
	v_add_f32_e32 v94, v94, v95
	v_add_f32_e32 v96, v96, v97
	v_add_f32_e32 v92, v92, v93
	v_add_f32_e32 v88, v88, v89
	v_add_f32_e32 v86, v86, v87
	v_add_f32_e32 v78, v78, v79
	v_add_f32_e32 v76, v76, v77
	v_add_f32_e32 v66, v66, v67
	v_add_f32_e32 v67, v94, v96
	v_add_f32_e32 v77, v88, v92
	v_add_f32_e32 v78, v78, v86
	v_add_f32_e32 v66, v66, v76
	v_add_f32_e32 v67, v77, v67
	v_add_f32_e32 v66, v66, v78
	v_add_f32_e32 v76, v66, v67
	ds_bpermute_b32 v77, v161, v76
	v_cvt_pk_bf16_f32 v66, v72, v73
	v_cvt_pk_bf16_f32 v67, v74, v75
	global_store_dwordx4 v[90:91], v[64:67], off
	s_waitcnt lgkmcnt(0)
	s_nop 0
	v_add_f32_e32 v64, v76, v77
	ds_bpermute_b32 v65, v160, v64
	v_cvt_pk_bf16_f32 v66, v68, v69
	v_cvt_pk_bf16_f32 v67, v70, v71
	v_cvt_pk_bf16_f32 v68, v82, v83
	v_cvt_pk_bf16_f32 v69, v84, v85
	global_store_dwordx4 v[90:91], v[66:69], off offset:256
	s_and_saveexec_b64 s[26:27], s[4:5]
	s_cbranch_execz .LBB0_720
	v_lshlrev_b64 v[66:67], 6, v[80:81]
	v_lshl_add_u64 v[66:67], s[16:17], 0, v[66:67]
	v_lshl_add_u64 v[66:67], s[24:25], 2, v[66:67]
	s_lshl_b32 s10, s40, 2
	v_lshl_add_u64 v[66:67], v[66:67], 0, s[10:11]
	s_waitcnt lgkmcnt(0)
	v_add_f32_e32 v64, v64, v65
	global_store_dword v[66:67], v64, off
.LBB0_720:
	s_or_b64 exec, exec, s[26:27]
	v_add_u32_e32 v64, 0x80, v150
	s_waitcnt lgkmcnt(0)
	v_ashrrev_i32_e32 v65, 31, v64
	v_lshlrev_b64 v[66:67], 11, v[64:65]
	v_lshl_add_u64 v[66:67], s[14:15], 0, v[66:67]
	v_lshl_add_u64 v[74:75], v[148:149], 1, v[66:67]
	s_nop 1
	v_mov_b32_e32 v66, v208
	v_mov_b32_e32 v67, v209
	v_mov_b32_e32 v68, v210
	v_mov_b32_e32 v69, v211
	v_mov_b32_e32 v70, v212
	v_mov_b32_e32 v71, v213
	v_mov_b32_e32 v72, v214
	v_mov_b32_e32 v73, v215
	v_lshlrev_b32_e32 v76, 16, v66
	v_and_b32_e32 v77, 0xffff0000, v66
	v_lshlrev_b32_e32 v66, 16, v67
	v_and_b32_e32 v67, 0xffff0000, v67
	v_lshlrev_b32_e32 v78, 16, v68
	v_and_b32_e32 v79, 0xffff0000, v68
	v_lshlrev_b32_e32 v68, 16, v69
	v_and_b32_e32 v69, 0xffff0000, v69
	v_lshlrev_b32_e32 v80, 16, v70
	v_and_b32_e32 v81, 0xffff0000, v70
	v_lshlrev_b32_e32 v70, 16, v71
	v_and_b32_e32 v71, 0xffff0000, v71
	v_lshlrev_b32_e32 v82, 16, v72
	v_and_b32_e32 v83, 0xffff0000, v72
	v_lshlrev_b32_e32 v72, 16, v73
	v_and_b32_e32 v73, 0xffff0000, v73
	v_pk_add_f32 v[60:61], v[60:61], v[76:77]
	v_pk_add_f32 v[62:63], v[62:63], v[66:67]
	v_pk_add_f32 v[56:57], v[56:57], v[78:79]
	v_pk_add_f32 v[58:59], v[58:59], v[68:69]
	v_pk_add_f32 v[52:53], v[52:53], v[80:81]
	v_pk_add_f32 v[54:55], v[54:55], v[70:71]
	v_pk_add_f32 v[66:67], v[48:49], v[82:83]
	v_pk_add_f32 v[68:69], v[50:51], v[72:73]
	v_cvt_pk_bf16_f32 v48, v60, v61
	v_cvt_pk_bf16_f32 v49, v62, v63
	v_pk_mul_f32 v[50:51], v[60:61], v[60:61]
	v_pk_mul_f32 v[60:61], v[62:63], v[62:63]
	v_pk_mul_f32 v[62:63], v[56:57], v[56:57]
	v_pk_mul_f32 v[70:71], v[58:59], v[58:59]
	v_pk_mul_f32 v[72:73], v[52:53], v[52:53]
	v_pk_mul_f32 v[76:77], v[54:55], v[54:55]
	v_pk_mul_f32 v[78:79], v[66:67], v[66:67]
	v_pk_mul_f32 v[80:81], v[68:69], v[68:69]
	v_add_f32_e32 v78, v78, v79
	v_add_f32_e32 v80, v80, v81
	v_add_f32_e32 v76, v76, v77
	v_add_f32_e32 v72, v72, v73
	v_add_f32_e32 v70, v70, v71
	v_add_f32_e32 v62, v62, v63
	v_add_f32_e32 v60, v60, v61
	v_add_f32_e32 v50, v50, v51
	v_add_f32_e32 v51, v78, v80
	v_add_f32_e32 v61, v72, v76
	v_add_f32_e32 v62, v62, v70
	v_add_f32_e32 v50, v50, v60
	v_add_f32_e32 v51, v61, v51
	v_add_f32_e32 v50, v50, v62
	v_add_f32_e32 v60, v50, v51
	ds_bpermute_b32 v61, v161, v60
	v_cvt_pk_bf16_f32 v50, v56, v57
	v_cvt_pk_bf16_f32 v51, v58, v59
	global_store_dwordx4 v[74:75], v[48:51], off
	s_waitcnt lgkmcnt(0)
	s_nop 0
	v_add_f32_e32 v48, v60, v61
	ds_bpermute_b32 v49, v160, v48
	v_cvt_pk_bf16_f32 v50, v52, v53
	v_cvt_pk_bf16_f32 v51, v54, v55
	v_cvt_pk_bf16_f32 v52, v66, v67
	v_cvt_pk_bf16_f32 v53, v68, v69
	global_store_dwordx4 v[74:75], v[50:53], off offset:256
	s_and_saveexec_b64 s[26:27], s[4:5]
	s_cbranch_execz .LBB0_722
	v_lshlrev_b64 v[50:51], 6, v[64:65]
	v_lshl_add_u64 v[50:51], s[16:17], 0, v[50:51]
	v_lshl_add_u64 v[50:51], s[24:25], 2, v[50:51]
	s_lshl_b32 s10, s40, 2
	v_lshl_add_u64 v[50:51], v[50:51], 0, s[10:11]
	s_waitcnt lgkmcnt(0)
	v_add_f32_e32 v48, v48, v49
	global_store_dword v[50:51], v48, off
.LBB0_722:
	s_or_b64 exec, exec, s[26:27]
	v_add_u32_e32 v48, 0x90, v150
	s_waitcnt lgkmcnt(0)
	v_ashrrev_i32_e32 v49, 31, v48
	v_lshlrev_b64 v[50:51], 11, v[48:49]
	v_lshl_add_u64 v[50:51], s[14:15], 0, v[50:51]
	v_lshl_add_u64 v[58:59], v[148:149], 1, v[50:51]
	s_nop 1
	v_mov_b32_e32 v50, v216
	v_mov_b32_e32 v51, v217
	v_mov_b32_e32 v52, v218
	v_mov_b32_e32 v53, v219
	v_mov_b32_e32 v54, v220
	v_mov_b32_e32 v55, v221
	v_mov_b32_e32 v56, v222
	v_mov_b32_e32 v57, v223
	v_lshlrev_b32_e32 v60, 16, v50
	v_and_b32_e32 v61, 0xffff0000, v50
	v_lshlrev_b32_e32 v50, 16, v51
	v_and_b32_e32 v51, 0xffff0000, v51
	v_lshlrev_b32_e32 v62, 16, v52
	v_and_b32_e32 v63, 0xffff0000, v52
	v_lshlrev_b32_e32 v52, 16, v53
	v_and_b32_e32 v53, 0xffff0000, v53
	v_lshlrev_b32_e32 v64, 16, v54
	v_and_b32_e32 v65, 0xffff0000, v54
	v_lshlrev_b32_e32 v54, 16, v55
	v_and_b32_e32 v55, 0xffff0000, v55
	v_lshlrev_b32_e32 v66, 16, v56
	v_and_b32_e32 v67, 0xffff0000, v56
	v_lshlrev_b32_e32 v56, 16, v57
	v_and_b32_e32 v57, 0xffff0000, v57
	v_pk_add_f32 v[44:45], v[44:45], v[60:61]
	v_pk_add_f32 v[46:47], v[46:47], v[50:51]
	v_pk_add_f32 v[40:41], v[40:41], v[62:63]
	v_pk_add_f32 v[42:43], v[42:43], v[52:53]
	v_pk_add_f32 v[36:37], v[36:37], v[64:65]
	v_pk_add_f32 v[38:39], v[38:39], v[54:55]
	v_pk_add_f32 v[50:51], v[32:33], v[66:67]
	v_pk_add_f32 v[52:53], v[34:35], v[56:57]
	v_cvt_pk_bf16_f32 v32, v44, v45
	v_cvt_pk_bf16_f32 v33, v46, v47
	v_pk_mul_f32 v[34:35], v[44:45], v[44:45]
	v_pk_mul_f32 v[44:45], v[46:47], v[46:47]
	v_pk_mul_f32 v[46:47], v[40:41], v[40:41]
	v_pk_mul_f32 v[54:55], v[42:43], v[42:43]
	v_pk_mul_f32 v[56:57], v[36:37], v[36:37]
	v_pk_mul_f32 v[60:61], v[38:39], v[38:39]
	v_pk_mul_f32 v[62:63], v[50:51], v[50:51]
	v_pk_mul_f32 v[64:65], v[52:53], v[52:53]
	v_add_f32_e32 v62, v62, v63
	v_add_f32_e32 v64, v64, v65
	v_add_f32_e32 v60, v60, v61
	v_add_f32_e32 v56, v56, v57
	v_add_f32_e32 v54, v54, v55
	v_add_f32_e32 v46, v46, v47
	v_add_f32_e32 v44, v44, v45
	v_add_f32_e32 v34, v34, v35
	v_add_f32_e32 v35, v62, v64
	v_add_f32_e32 v45, v56, v60
	v_add_f32_e32 v46, v46, v54
	v_add_f32_e32 v34, v34, v44
	v_add_f32_e32 v35, v45, v35
	v_add_f32_e32 v34, v34, v46
	v_add_f32_e32 v44, v34, v35
	ds_bpermute_b32 v45, v161, v44
	v_cvt_pk_bf16_f32 v34, v40, v41
	v_cvt_pk_bf16_f32 v35, v42, v43
	global_store_dwordx4 v[58:59], v[32:35], off
	s_waitcnt lgkmcnt(0)
	s_nop 0
	v_add_f32_e32 v32, v44, v45
	ds_bpermute_b32 v33, v160, v32
	v_cvt_pk_bf16_f32 v34, v36, v37
	v_cvt_pk_bf16_f32 v35, v38, v39
	v_cvt_pk_bf16_f32 v36, v50, v51
	v_cvt_pk_bf16_f32 v37, v52, v53
	global_store_dwordx4 v[58:59], v[34:37], off offset:256
	s_and_saveexec_b64 s[26:27], s[4:5]
	s_cbranch_execz .LBB0_724
	v_lshlrev_b64 v[34:35], 6, v[48:49]
	v_lshl_add_u64 v[34:35], s[16:17], 0, v[34:35]
	v_lshl_add_u64 v[34:35], s[24:25], 2, v[34:35]
	s_lshl_b32 s10, s40, 2
	v_lshl_add_u64 v[34:35], v[34:35], 0, s[10:11]
	s_waitcnt lgkmcnt(0)
	v_add_f32_e32 v32, v32, v33
	global_store_dword v[34:35], v32, off
.LBB0_724:
	s_or_b64 exec, exec, s[26:27]
	v_add_u32_e32 v32, 0xa0, v150
	s_waitcnt lgkmcnt(0)
	v_ashrrev_i32_e32 v33, 31, v32
	v_lshlrev_b64 v[34:35], 11, v[32:33]
	v_lshl_add_u64 v[34:35], s[14:15], 0, v[34:35]
	v_lshl_add_u64 v[42:43], v[148:149], 1, v[34:35]
	s_nop 1
	v_mov_b32_e32 v34, v224
	v_mov_b32_e32 v35, v225
	v_mov_b32_e32 v36, v226
	v_mov_b32_e32 v37, v227
	v_mov_b32_e32 v38, v228
	v_mov_b32_e32 v39, v229
	v_mov_b32_e32 v40, v230
	v_mov_b32_e32 v41, v231
	v_lshlrev_b32_e32 v44, 16, v34
	v_and_b32_e32 v45, 0xffff0000, v34
	v_lshlrev_b32_e32 v34, 16, v35
	v_and_b32_e32 v35, 0xffff0000, v35
	v_lshlrev_b32_e32 v46, 16, v36
	v_and_b32_e32 v47, 0xffff0000, v36
	v_lshlrev_b32_e32 v36, 16, v37
	v_and_b32_e32 v37, 0xffff0000, v37
	v_lshlrev_b32_e32 v48, 16, v38
	v_and_b32_e32 v49, 0xffff0000, v38
	v_lshlrev_b32_e32 v38, 16, v39
	v_and_b32_e32 v39, 0xffff0000, v39
	v_lshlrev_b32_e32 v50, 16, v40
	v_and_b32_e32 v51, 0xffff0000, v40
	v_lshlrev_b32_e32 v40, 16, v41
	v_and_b32_e32 v41, 0xffff0000, v41
	v_pk_add_f32 v[28:29], v[28:29], v[44:45]
	v_pk_add_f32 v[30:31], v[30:31], v[34:35]
	v_pk_add_f32 v[24:25], v[24:25], v[46:47]
	v_pk_add_f32 v[26:27], v[26:27], v[36:37]
	v_pk_add_f32 v[20:21], v[20:21], v[48:49]
	v_pk_add_f32 v[22:23], v[22:23], v[38:39]
	v_pk_add_f32 v[34:35], v[16:17], v[50:51]
	v_pk_add_f32 v[36:37], v[18:19], v[40:41]
	v_cvt_pk_bf16_f32 v16, v28, v29
	v_cvt_pk_bf16_f32 v17, v30, v31
	v_pk_mul_f32 v[18:19], v[28:29], v[28:29]
	v_pk_mul_f32 v[28:29], v[30:31], v[30:31]
	v_pk_mul_f32 v[30:31], v[24:25], v[24:25]
	v_pk_mul_f32 v[38:39], v[26:27], v[26:27]
	v_pk_mul_f32 v[40:41], v[20:21], v[20:21]
	v_pk_mul_f32 v[44:45], v[22:23], v[22:23]
	v_pk_mul_f32 v[46:47], v[34:35], v[34:35]
	v_pk_mul_f32 v[48:49], v[36:37], v[36:37]
	v_add_f32_e32 v46, v46, v47
	v_add_f32_e32 v48, v48, v49
	v_add_f32_e32 v44, v44, v45
	v_add_f32_e32 v40, v40, v41
	v_add_f32_e32 v38, v38, v39
	v_add_f32_e32 v30, v30, v31
	v_add_f32_e32 v28, v28, v29
	v_add_f32_e32 v18, v18, v19
	v_add_f32_e32 v19, v46, v48
	v_add_f32_e32 v29, v40, v44
	v_add_f32_e32 v30, v30, v38
	v_add_f32_e32 v18, v18, v28
	v_add_f32_e32 v19, v29, v19
	v_add_f32_e32 v18, v18, v30
	v_add_f32_e32 v28, v18, v19
	ds_bpermute_b32 v29, v161, v28
	v_cvt_pk_bf16_f32 v18, v24, v25
	v_cvt_pk_bf16_f32 v19, v26, v27
	global_store_dwordx4 v[42:43], v[16:19], off
	s_waitcnt lgkmcnt(0)
	s_nop 0
	v_add_f32_e32 v16, v28, v29
	ds_bpermute_b32 v17, v160, v16
	v_cvt_pk_bf16_f32 v18, v20, v21
	v_cvt_pk_bf16_f32 v19, v22, v23
	v_cvt_pk_bf16_f32 v20, v34, v35
	v_cvt_pk_bf16_f32 v21, v36, v37
	global_store_dwordx4 v[42:43], v[18:21], off offset:256
	s_and_saveexec_b64 s[26:27], s[4:5]
	s_cbranch_execz .LBB0_726
	v_lshlrev_b64 v[18:19], 6, v[32:33]
	v_lshl_add_u64 v[18:19], s[16:17], 0, v[18:19]
	v_lshl_add_u64 v[18:19], s[24:25], 2, v[18:19]
	s_lshl_b32 s10, s40, 2
	v_lshl_add_u64 v[18:19], v[18:19], 0, s[10:11]
	s_waitcnt lgkmcnt(0)
	v_add_f32_e32 v16, v16, v17
	global_store_dword v[18:19], v16, off
.LBB0_726:
	s_or_b64 exec, exec, s[26:27]
	v_add_u32_e32 v16, 0xb0, v150
	s_waitcnt lgkmcnt(0)
	v_ashrrev_i32_e32 v17, 31, v16
	v_lshlrev_b64 v[18:19], 11, v[16:17]
	v_lshl_add_u64 v[18:19], s[14:15], 0, v[18:19]
	v_lshl_add_u64 v[26:27], v[148:149], 1, v[18:19]
	s_nop 1
	v_mov_b32_e32 v18, v238
	v_mov_b32_e32 v19, v239
	v_mov_b32_e32 v20, v240
	v_mov_b32_e32 v21, v241
	v_mov_b32_e32 v22, v242
	v_mov_b32_e32 v23, v243
	v_mov_b32_e32 v24, v244
	v_mov_b32_e32 v25, v245
	v_lshlrev_b32_e32 v28, 16, v18
	v_and_b32_e32 v29, 0xffff0000, v18
	v_lshlrev_b32_e32 v18, 16, v19
	v_and_b32_e32 v19, 0xffff0000, v19
	v_lshlrev_b32_e32 v30, 16, v20
	v_and_b32_e32 v31, 0xffff0000, v20
	v_lshlrev_b32_e32 v20, 16, v21
	v_and_b32_e32 v21, 0xffff0000, v21
	v_lshlrev_b32_e32 v32, 16, v22
	v_and_b32_e32 v33, 0xffff0000, v22
	v_lshlrev_b32_e32 v22, 16, v23
	v_and_b32_e32 v23, 0xffff0000, v23
	v_lshlrev_b32_e32 v34, 16, v24
	v_and_b32_e32 v35, 0xffff0000, v24
	v_lshlrev_b32_e32 v24, 16, v25
	v_and_b32_e32 v25, 0xffff0000, v25
	v_pk_add_f32 v[12:13], v[12:13], v[28:29]
	v_pk_add_f32 v[14:15], v[14:15], v[18:19]
	v_pk_add_f32 v[8:9], v[8:9], v[30:31]
	v_pk_add_f32 v[10:11], v[10:11], v[20:21]
	v_pk_add_f32 v[4:5], v[4:5], v[32:33]
	v_pk_add_f32 v[6:7], v[6:7], v[22:23]
	v_pk_add_f32 v[18:19], v[0:1], v[34:35]
	v_pk_add_f32 v[20:21], v[2:3], v[24:25]
	v_cvt_pk_bf16_f32 v0, v12, v13
	v_cvt_pk_bf16_f32 v1, v14, v15
	v_pk_mul_f32 v[2:3], v[12:13], v[12:13]
	v_pk_mul_f32 v[12:13], v[14:15], v[14:15]
	v_pk_mul_f32 v[14:15], v[8:9], v[8:9]
	v_pk_mul_f32 v[22:23], v[10:11], v[10:11]
	v_pk_mul_f32 v[24:25], v[4:5], v[4:5]
	v_pk_mul_f32 v[28:29], v[6:7], v[6:7]
	v_pk_mul_f32 v[30:31], v[18:19], v[18:19]
	v_pk_mul_f32 v[32:33], v[20:21], v[20:21]
	v_add_f32_e32 v30, v30, v31
	v_add_f32_e32 v32, v32, v33
	v_add_f32_e32 v28, v28, v29
	v_add_f32_e32 v24, v24, v25
	v_add_f32_e32 v22, v22, v23
	v_add_f32_e32 v14, v14, v15
	v_add_f32_e32 v12, v12, v13
	v_add_f32_e32 v2, v2, v3
	v_add_f32_e32 v3, v30, v32
	v_add_f32_e32 v13, v24, v28
	v_add_f32_e32 v14, v14, v22
	v_add_f32_e32 v2, v2, v12
	v_add_f32_e32 v3, v13, v3
	v_add_f32_e32 v2, v2, v14
	v_add_f32_e32 v12, v2, v3
	ds_bpermute_b32 v13, v161, v12
	v_cvt_pk_bf16_f32 v2, v8, v9
	v_cvt_pk_bf16_f32 v3, v10, v11
	global_store_dwordx4 v[26:27], v[0:3], off
	s_waitcnt lgkmcnt(0)
	s_nop 0
	v_add_f32_e32 v0, v12, v13
	ds_bpermute_b32 v1, v160, v0
	v_cvt_pk_bf16_f32 v2, v4, v5
	v_cvt_pk_bf16_f32 v3, v6, v7
	v_cvt_pk_bf16_f32 v4, v18, v19
	v_cvt_pk_bf16_f32 v5, v20, v21
	global_store_dwordx4 v[26:27], v[2:5], off offset:256
	s_and_saveexec_b64 s[26:27], s[4:5]
	s_cbranch_execz .LBB0_728
	v_lshlrev_b64 v[2:3], 6, v[16:17]
	v_lshl_add_u64 v[2:3], s[16:17], 0, v[2:3]
	v_lshl_add_u64 v[2:3], s[24:25], 2, v[2:3]
	s_lshl_b32 s10, s40, 2
	v_lshl_add_u64 v[2:3], v[2:3], 0, s[10:11]
	s_waitcnt lgkmcnt(0)
	v_add_f32_e32 v0, v0, v1
	global_store_dword v[2:3], v0, off

.LBB0_1151:
	v_lshl_add_u32 v150, s28, 8, v131
	v_ashrrev_i32_e32 v151, 31, v150
	v_lshl_or_b32 v148, s8, 8, v153
	v_lshlrev_b64 v[158:159], 11, v[150:151]
	v_ashrrev_i32_e32 v149, 31, v148
	v_lshl_add_u64 v[158:159], s[12:13], 0, v[158:159]
	v_lshl_add_u64 v[168:169], v[148:149], 1, v[158:159]
	global_load_dwordx4 v[160:163], v[168:169], off
	global_load_dwordx4 v[164:167], v[168:169], off offset:256
	s_mov_b64 s[100:101], 0x8000
	v_lshl_add_u64 v[232:233], v[168:169], 0, s[100:101]
	global_load_dwordx4 v[184:187], v[232:233], off
	global_load_dwordx4 v[188:191], v[232:233], off offset:256
	s_mov_b64 s[100:101], 0x10000
	v_lshl_add_u64 v[232:233], v[168:169], 0, s[100:101]
	global_load_dwordx4 v[192:195], v[232:233], off
	global_load_dwordx4 v[196:199], v[232:233], off offset:256
	s_mov_b64 s[100:101], 0x18000
	v_lshl_add_u64 v[232:233], v[168:169], 0, s[100:101]
	global_load_dwordx4 v[200:203], v[232:233], off
	global_load_dwordx4 v[204:207], v[232:233], off offset:256
	s_mov_b64 s[100:101], 0x40000
	v_lshl_add_u64 v[232:233], v[168:169], 0, s[100:101]
	global_load_dwordx4 v[208:211], v[232:233], off
	global_load_dwordx4 v[212:215], v[232:233], off offset:256
	s_mov_b64 s[100:101], 0x48000
	v_lshl_add_u64 v[232:233], v[168:169], 0, s[100:101]
	global_load_dwordx4 v[216:219], v[232:233], off
	global_load_dwordx4 v[220:223], v[232:233], off offset:256
	s_mov_b64 s[100:101], 0x50000
	v_lshl_add_u64 v[232:233], v[168:169], 0, s[100:101]
	global_load_dwordx4 v[224:227], v[232:233], off
	global_load_dwordx4 v[228:231], v[232:233], off offset:256
	s_mov_b64 s[100:101], 0x58000
	v_lshl_add_u64 v[232:233], v[168:169], 0, s[100:101]
	global_load_dwordx4 v[238:241], v[232:233], off
	global_load_dwordx4 v[242:245], v[232:233], off offset:256
	v_and_b32_e32 v159, 64, v157
	v_xor_b32_e32 v158, 16, v157
	v_add_u32_e32 v159, 64, v159
	v_xor_b32_e32 v170, 32, v157
	v_cmp_lt_i32_e32 vcc, v158, v159
	s_lshl_b32 s28, s8, 2
	s_ashr_i32 s29, s28, 31
	v_cndmask_b32_e32 v158, v157, v158, vcc
	v_cmp_lt_i32_e32 vcc, v170, v159
	v_lshlrev_b32_e32 v159, 2, v158
	s_waitcnt vmcnt(0)
	v_and_b32_e32 v171, 0xffff0000, v160
	v_cndmask_b32_e32 v170, v157, v170, vcc
	v_lshlrev_b32_e32 v158, 2, v170
	v_lshlrev_b32_e32 v170, 16, v160
	v_lshlrev_b32_e32 v160, 16, v161
	v_and_b32_e32 v161, 0xffff0000, v161
	v_lshlrev_b32_e32 v172, 16, v162
	v_and_b32_e32 v173, 0xffff0000, v162
	v_lshlrev_b32_e32 v162, 16, v163
	v_and_b32_e32 v163, 0xffff0000, v163
	v_lshlrev_b32_e32 v174, 16, v164
	v_and_b32_e32 v175, 0xffff0000, v164
	v_lshlrev_b32_e32 v164, 16, v165
	v_and_b32_e32 v165, 0xffff0000, v165
	v_lshlrev_b32_e32 v176, 16, v166
	v_and_b32_e32 v177, 0xffff0000, v166
	v_lshlrev_b32_e32 v166, 16, v167
	v_and_b32_e32 v167, 0xffff0000, v167
	v_pk_add_f32 v[124:125], v[124:125], v[170:171]
	v_pk_add_f32 v[126:127], v[126:127], v[160:161]
	v_pk_add_f32 v[120:121], v[120:121], v[172:173]
	v_pk_add_f32 v[122:123], v[122:123], v[162:163]
	v_pk_add_f32 v[116:117], v[116:117], v[174:175]
	v_pk_add_f32 v[118:119], v[118:119], v[164:165]
	v_pk_add_f32 v[160:161], v[112:113], v[176:177]
	v_pk_add_f32 v[162:163], v[114:115], v[166:167]
	v_cvt_pk_bf16_f32 v112, v124, v125
	v_cvt_pk_bf16_f32 v113, v126, v127
	v_pk_mul_f32 v[114:115], v[124:125], v[124:125]
	v_pk_mul_f32 v[124:125], v[126:127], v[126:127]
	v_pk_mul_f32 v[126:127], v[120:121], v[120:121]
	v_pk_mul_f32 v[164:165], v[122:123], v[122:123]
	v_pk_mul_f32 v[166:167], v[116:117], v[116:117]
	v_pk_mul_f32 v[170:171], v[118:119], v[118:119]
	v_pk_mul_f32 v[172:173], v[160:161], v[160:161]
	v_pk_mul_f32 v[174:175], v[162:163], v[162:163]
	v_add_f32_e32 v172, v172, v173
	v_add_f32_e32 v174, v174, v175
	v_add_f32_e32 v170, v170, v171
	v_add_f32_e32 v166, v166, v167
	v_add_f32_e32 v164, v164, v165
	v_add_f32_e32 v126, v126, v127
	v_add_f32_e32 v124, v124, v125
	v_add_f32_e32 v114, v114, v115
	v_add_f32_e32 v115, v172, v174
	v_add_f32_e32 v125, v166, v170
	v_add_f32_e32 v126, v126, v164
	v_add_f32_e32 v114, v114, v124
	v_add_f32_e32 v115, v125, v115
	v_add_f32_e32 v114, v114, v126
	v_add_f32_e32 v124, v114, v115
	ds_bpermute_b32 v125, v159, v124
	v_cvt_pk_bf16_f32 v114, v120, v121
	v_cvt_pk_bf16_f32 v115, v122, v123
	global_store_dwordx4 v[168:169], v[112:115], off
	s_waitcnt lgkmcnt(0)
	s_nop 0
	v_add_f32_e32 v112, v124, v125
	ds_bpermute_b32 v113, v158, v112
	v_cvt_pk_bf16_f32 v114, v116, v117
	v_cvt_pk_bf16_f32 v115, v118, v119
	v_cvt_pk_bf16_f32 v116, v160, v161
	v_cvt_pk_bf16_f32 v117, v162, v163
	global_store_dwordx4 v[168:169], v[114:117], off offset:256
	s_and_saveexec_b64 s[30:31], s[4:5]
	s_cbranch_execz .LBB0_1153
	v_lshlrev_b64 v[114:115], 6, v[150:151]
	v_lshl_add_u64 v[114:115], s[14:15], 0, v[114:115]
	v_lshl_add_u64 v[114:115], s[28:29], 2, v[114:115]
	s_lshl_b32 s8, s46, 2
	v_lshl_add_u64 v[114:115], v[114:115], 0, s[8:9]
	s_waitcnt lgkmcnt(0)
	v_add_f32_e32 v112, v112, v113
	global_store_dword v[114:115], v112, off
.LBB0_1153:
	s_or_b64 exec, exec, s[30:31]
	v_or_b32_e32 v112, 16, v150
	s_waitcnt lgkmcnt(0)
	v_ashrrev_i32_e32 v113, 31, v112
	v_lshlrev_b64 v[114:115], 11, v[112:113]
	v_lshl_add_u64 v[114:115], s[12:13], 0, v[114:115]
	v_lshl_add_u64 v[122:123], v[148:149], 1, v[114:115]
	s_nop 1
	v_mov_b32_e32 v114, v184
	v_mov_b32_e32 v115, v185
	v_mov_b32_e32 v116, v186
	v_mov_b32_e32 v117, v187
	v_mov_b32_e32 v118, v188
	v_mov_b32_e32 v119, v189
	v_mov_b32_e32 v120, v190
	v_mov_b32_e32 v121, v191
	v_lshlrev_b32_e32 v124, 16, v114
	v_and_b32_e32 v125, 0xffff0000, v114
	v_lshlrev_b32_e32 v114, 16, v115
	v_and_b32_e32 v115, 0xffff0000, v115
	v_lshlrev_b32_e32 v126, 16, v116
	v_and_b32_e32 v127, 0xffff0000, v116
	v_lshlrev_b32_e32 v116, 16, v117
	v_and_b32_e32 v117, 0xffff0000, v117
	v_lshlrev_b32_e32 v160, 16, v118
	v_and_b32_e32 v161, 0xffff0000, v118
	v_lshlrev_b32_e32 v118, 16, v119
	v_and_b32_e32 v119, 0xffff0000, v119
	v_lshlrev_b32_e32 v162, 16, v120
	v_and_b32_e32 v163, 0xffff0000, v120
	v_lshlrev_b32_e32 v120, 16, v121
	v_and_b32_e32 v121, 0xffff0000, v121
	v_pk_add_f32 v[108:109], v[108:109], v[124:125]
	v_pk_add_f32 v[110:111], v[110:111], v[114:115]
	v_pk_add_f32 v[104:105], v[104:105], v[126:127]
	v_pk_add_f32 v[106:107], v[106:107], v[116:117]
	v_pk_add_f32 v[100:101], v[100:101], v[160:161]
	v_pk_add_f32 v[102:103], v[102:103], v[118:119]
	v_pk_add_f32 v[114:115], v[96:97], v[162:163]
	v_pk_add_f32 v[116:117], v[98:99], v[120:121]
	v_cvt_pk_bf16_f32 v96, v108, v109
	v_cvt_pk_bf16_f32 v97, v110, v111
	v_pk_mul_f32 v[98:99], v[108:109], v[108:109]
	v_pk_mul_f32 v[108:109], v[110:111], v[110:111]
	v_pk_mul_f32 v[110:111], v[104:105], v[104:105]
	v_pk_mul_f32 v[118:119], v[106:107], v[106:107]
	v_pk_mul_f32 v[120:121], v[100:101], v[100:101]
	v_pk_mul_f32 v[124:125], v[102:103], v[102:103]
	v_pk_mul_f32 v[126:127], v[114:115], v[114:115]
	v_pk_mul_f32 v[160:161], v[116:117], v[116:117]
	v_add_f32_e32 v126, v126, v127
	v_add_f32_e32 v151, v160, v161
	v_add_f32_e32 v124, v124, v125
	v_add_f32_e32 v120, v120, v121
	v_add_f32_e32 v118, v118, v119
	v_add_f32_e32 v110, v110, v111
	v_add_f32_e32 v108, v108, v109
	v_add_f32_e32 v98, v98, v99
	v_add_f32_e32 v99, v126, v151
	v_add_f32_e32 v109, v120, v124
	v_add_f32_e32 v110, v110, v118
	v_add_f32_e32 v98, v98, v108
	v_add_f32_e32 v99, v109, v99
	v_add_f32_e32 v98, v98, v110
	v_add_f32_e32 v108, v98, v99
	ds_bpermute_b32 v109, v159, v108
	v_cvt_pk_bf16_f32 v98, v104, v105
	v_cvt_pk_bf16_f32 v99, v106, v107
	global_store_dwordx4 v[122:123], v[96:99], off
	s_waitcnt lgkmcnt(0)
	s_nop 0
	v_add_f32_e32 v96, v108, v109
	ds_bpermute_b32 v97, v158, v96
	v_cvt_pk_bf16_f32 v98, v100, v101
	v_cvt_pk_bf16_f32 v99, v102, v103
	v_cvt_pk_bf16_f32 v100, v114, v115
	v_cvt_pk_bf16_f32 v101, v116, v117
	global_store_dwordx4 v[122:123], v[98:101], off offset:256
	s_and_saveexec_b64 s[30:31], s[4:5]
	s_cbranch_execz .LBB0_1155
	v_lshlrev_b64 v[98:99], 6, v[112:113]
	v_lshl_add_u64 v[98:99], s[14:15], 0, v[98:99]
	v_lshl_add_u64 v[98:99], s[28:29], 2, v[98:99]
	s_lshl_b32 s8, s46, 2
	v_lshl_add_u64 v[98:99], v[98:99], 0, s[8:9]
	s_waitcnt lgkmcnt(0)
	v_add_f32_e32 v96, v96, v97
	global_store_dword v[98:99], v96, off
.LBB0_1155:
	s_or_b64 exec, exec, s[30:31]
	v_or_b32_e32 v96, 32, v150
	s_waitcnt lgkmcnt(0)
	v_ashrrev_i32_e32 v97, 31, v96
	v_lshlrev_b64 v[98:99], 11, v[96:97]
	v_lshl_add_u64 v[98:99], s[12:13], 0, v[98:99]
	v_lshl_add_u64 v[106:107], v[148:149], 1, v[98:99]
	s_nop 1
	v_mov_b32_e32 v98, v192
	v_mov_b32_e32 v99, v193
	v_mov_b32_e32 v100, v194
	v_mov_b32_e32 v101, v195
	v_mov_b32_e32 v102, v196
	v_mov_b32_e32 v103, v197
	v_mov_b32_e32 v104, v198
	v_mov_b32_e32 v105, v199
	v_lshlrev_b32_e32 v108, 16, v98
	v_and_b32_e32 v109, 0xffff0000, v98
	v_lshlrev_b32_e32 v98, 16, v99
	v_and_b32_e32 v99, 0xffff0000, v99
	v_lshlrev_b32_e32 v110, 16, v100
	v_and_b32_e32 v111, 0xffff0000, v100
	v_lshlrev_b32_e32 v100, 16, v101
	v_and_b32_e32 v101, 0xffff0000, v101
	v_lshlrev_b32_e32 v112, 16, v102
	v_and_b32_e32 v113, 0xffff0000, v102
	v_lshlrev_b32_e32 v102, 16, v103
	v_and_b32_e32 v103, 0xffff0000, v103
	v_lshlrev_b32_e32 v114, 16, v104
	v_and_b32_e32 v115, 0xffff0000, v104
	v_lshlrev_b32_e32 v104, 16, v105
	v_and_b32_e32 v105, 0xffff0000, v105
	v_pk_add_f32 v[92:93], v[92:93], v[108:109]
	v_pk_add_f32 v[94:95], v[94:95], v[98:99]
	v_pk_add_f32 v[88:89], v[88:89], v[110:111]
	v_pk_add_f32 v[90:91], v[90:91], v[100:101]
	v_pk_add_f32 v[84:85], v[84:85], v[112:113]
	v_pk_add_f32 v[86:87], v[86:87], v[102:103]
	v_pk_add_f32 v[98:99], v[80:81], v[114:115]
	v_pk_add_f32 v[100:101], v[82:83], v[104:105]
	v_cvt_pk_bf16_f32 v80, v92, v93
	v_cvt_pk_bf16_f32 v81, v94, v95
	v_pk_mul_f32 v[82:83], v[92:93], v[92:93]
	v_pk_mul_f32 v[92:93], v[94:95], v[94:95]
	v_pk_mul_f32 v[94:95], v[88:89], v[88:89]
	v_pk_mul_f32 v[102:103], v[90:91], v[90:91]
	v_pk_mul_f32 v[104:105], v[84:85], v[84:85]
	v_pk_mul_f32 v[108:109], v[86:87], v[86:87]
	v_pk_mul_f32 v[110:111], v[98:99], v[98:99]
	v_pk_mul_f32 v[112:113], v[100:101], v[100:101]
	v_add_f32_e32 v110, v110, v111
	v_add_f32_e32 v112, v112, v113
	v_add_f32_e32 v108, v108, v109
	v_add_f32_e32 v104, v104, v105
	v_add_f32_e32 v102, v102, v103
	v_add_f32_e32 v94, v94, v95
	v_add_f32_e32 v92, v92, v93
	v_add_f32_e32 v82, v82, v83
	v_add_f32_e32 v83, v110, v112
	v_add_f32_e32 v93, v104, v108
	v_add_f32_e32 v94, v94, v102
	v_add_f32_e32 v82, v82, v92
	v_add_f32_e32 v83, v93, v83
	v_add_f32_e32 v82, v82, v94
	v_add_f32_e32 v92, v82, v83
	ds_bpermute_b32 v93, v159, v92
	v_cvt_pk_bf16_f32 v82, v88, v89
	v_cvt_pk_bf16_f32 v83, v90, v91
	global_store_dwordx4 v[106:107], v[80:83], off
	s_waitcnt lgkmcnt(0)
	s_nop 0
	v_add_f32_e32 v80, v92, v93
	ds_bpermute_b32 v81, v158, v80
	v_cvt_pk_bf16_f32 v82, v84, v85
	v_cvt_pk_bf16_f32 v83, v86, v87
	v_cvt_pk_bf16_f32 v84, v98, v99
	v_cvt_pk_bf16_f32 v85, v100, v101
	global_store_dwordx4 v[106:107], v[82:85], off offset:256
	s_and_saveexec_b64 s[30:31], s[4:5]
	s_cbranch_execz .LBB0_1157
	v_lshlrev_b64 v[82:83], 6, v[96:97]
	v_lshl_add_u64 v[82:83], s[14:15], 0, v[82:83]
	v_lshl_add_u64 v[82:83], s[28:29], 2, v[82:83]
	s_lshl_b32 s8, s46, 2
	v_lshl_add_u64 v[82:83], v[82:83], 0, s[8:9]
	s_waitcnt lgkmcnt(0)
	v_add_f32_e32 v80, v80, v81
	global_store_dword v[82:83], v80, off
.LBB0_1157:
	s_or_b64 exec, exec, s[30:31]
	v_or_b32_e32 v80, 48, v150
	s_waitcnt lgkmcnt(0)
	v_ashrrev_i32_e32 v81, 31, v80
	v_lshlrev_b64 v[82:83], 11, v[80:81]
	v_lshl_add_u64 v[82:83], s[12:13], 0, v[82:83]
	v_lshl_add_u64 v[90:91], v[148:149], 1, v[82:83]
	s_nop 1
	v_mov_b32_e32 v82, v200
	v_mov_b32_e32 v83, v201
	v_mov_b32_e32 v84, v202
	v_mov_b32_e32 v85, v203
	v_mov_b32_e32 v86, v204
	v_mov_b32_e32 v87, v205
	v_mov_b32_e32 v88, v206
	v_mov_b32_e32 v89, v207
	v_lshlrev_b32_e32 v92, 16, v82
	v_and_b32_e32 v93, 0xffff0000, v82
	v_lshlrev_b32_e32 v82, 16, v83
	v_and_b32_e32 v83, 0xffff0000, v83
	v_lshlrev_b32_e32 v94, 16, v84
	v_and_b32_e32 v95, 0xffff0000, v84
	v_lshlrev_b32_e32 v84, 16, v85
	v_and_b32_e32 v85, 0xffff0000, v85
	v_lshlrev_b32_e32 v96, 16, v86
	v_and_b32_e32 v97, 0xffff0000, v86
	v_lshlrev_b32_e32 v86, 16, v87
	v_and_b32_e32 v87, 0xffff0000, v87
	v_lshlrev_b32_e32 v98, 16, v88
	v_and_b32_e32 v99, 0xffff0000, v88
	v_lshlrev_b32_e32 v88, 16, v89
	v_and_b32_e32 v89, 0xffff0000, v89
	v_pk_add_f32 v[76:77], v[76:77], v[92:93]
	v_pk_add_f32 v[78:79], v[78:79], v[82:83]
	v_pk_add_f32 v[72:73], v[72:73], v[94:95]
	v_pk_add_f32 v[74:75], v[74:75], v[84:85]
	v_pk_add_f32 v[68:69], v[68:69], v[96:97]
	v_pk_add_f32 v[70:71], v[70:71], v[86:87]
	v_pk_add_f32 v[82:83], v[64:65], v[98:99]
	v_pk_add_f32 v[84:85], v[66:67], v[88:89]
	v_cvt_pk_bf16_f32 v64, v76, v77
	v_cvt_pk_bf16_f32 v65, v78, v79
	v_pk_mul_f32 v[66:67], v[76:77], v[76:77]
	v_pk_mul_f32 v[76:77], v[78:79], v[78:79]
	v_pk_mul_f32 v[78:79], v[72:73], v[72:73]
	v_pk_mul_f32 v[86:87], v[74:75], v[74:75]
	v_pk_mul_f32 v[88:89], v[68:69], v[68:69]
	v_pk_mul_f32 v[92:93], v[70:71], v[70:71]
	v_pk_mul_f32 v[94:95], v[82:83], v[82:83]
	v_pk_mul_f32 v[96:97], v[84:85], v[84:85]
	v_add_f32_e32 v94, v94, v95
	v_add_f32_e32 v96, v96, v97
	v_add_f32_e32 v92, v92, v93
	v_add_f32_e32 v88, v88, v89
	v_add_f32_e32 v86, v86, v87
	v_add_f32_e32 v78, v78, v79
	v_add_f32_e32 v76, v76, v77
	v_add_f32_e32 v66, v66, v67
	v_add_f32_e32 v67, v94, v96
	v_add_f32_e32 v77, v88, v92
	v_add_f32_e32 v78, v78, v86
	v_add_f32_e32 v66, v66, v76
	v_add_f32_e32 v67, v77, v67
	v_add_f32_e32 v66, v66, v78
	v_add_f32_e32 v76, v66, v67
	ds_bpermute_b32 v77, v159, v76
	v_cvt_pk_bf16_f32 v66, v72, v73
	v_cvt_pk_bf16_f32 v67, v74, v75
	global_store_dwordx4 v[90:91], v[64:67], off
	s_waitcnt lgkmcnt(0)
	s_nop 0
	v_add_f32_e32 v64, v76, v77
	ds_bpermute_b32 v65, v158, v64
	v_cvt_pk_bf16_f32 v66, v68, v69
	v_cvt_pk_bf16_f32 v67, v70, v71
	v_cvt_pk_bf16_f32 v68, v82, v83
	v_cvt_pk_bf16_f32 v69, v84, v85
	global_store_dwordx4 v[90:91], v[66:69], off offset:256
	s_and_saveexec_b64 s[30:31], s[4:5]
	s_cbranch_execz .LBB0_1159
	v_lshlrev_b64 v[66:67], 6, v[80:81]
	v_lshl_add_u64 v[66:67], s[14:15], 0, v[66:67]
	v_lshl_add_u64 v[66:67], s[28:29], 2, v[66:67]
	s_lshl_b32 s8, s46, 2
	v_lshl_add_u64 v[66:67], v[66:67], 0, s[8:9]
	s_waitcnt lgkmcnt(0)
	v_add_f32_e32 v64, v64, v65
	global_store_dword v[66:67], v64, off
.LBB0_1159:
	s_or_b64 exec, exec, s[30:31]
	v_add_u32_e32 v64, 0x80, v150
	s_waitcnt lgkmcnt(0)
	v_ashrrev_i32_e32 v65, 31, v64
	v_lshlrev_b64 v[66:67], 11, v[64:65]
	v_lshl_add_u64 v[66:67], s[12:13], 0, v[66:67]
	v_lshl_add_u64 v[74:75], v[148:149], 1, v[66:67]
	s_nop 1
	v_mov_b32_e32 v66, v208
	v_mov_b32_e32 v67, v209
	v_mov_b32_e32 v68, v210
	v_mov_b32_e32 v69, v211
	v_mov_b32_e32 v70, v212
	v_mov_b32_e32 v71, v213
	v_mov_b32_e32 v72, v214
	v_mov_b32_e32 v73, v215
	v_lshlrev_b32_e32 v76, 16, v66
	v_and_b32_e32 v77, 0xffff0000, v66
	v_lshlrev_b32_e32 v66, 16, v67
	v_and_b32_e32 v67, 0xffff0000, v67
	v_lshlrev_b32_e32 v78, 16, v68
	v_and_b32_e32 v79, 0xffff0000, v68
	v_lshlrev_b32_e32 v68, 16, v69
	v_and_b32_e32 v69, 0xffff0000, v69
	v_lshlrev_b32_e32 v80, 16, v70
	v_and_b32_e32 v81, 0xffff0000, v70
	v_lshlrev_b32_e32 v70, 16, v71
	v_and_b32_e32 v71, 0xffff0000, v71
	v_lshlrev_b32_e32 v82, 16, v72
	v_and_b32_e32 v83, 0xffff0000, v72
	v_lshlrev_b32_e32 v72, 16, v73
	v_and_b32_e32 v73, 0xffff0000, v73
	v_pk_add_f32 v[60:61], v[60:61], v[76:77]
	v_pk_add_f32 v[62:63], v[62:63], v[66:67]
	v_pk_add_f32 v[56:57], v[56:57], v[78:79]
	v_pk_add_f32 v[58:59], v[58:59], v[68:69]
	v_pk_add_f32 v[52:53], v[52:53], v[80:81]
	v_pk_add_f32 v[54:55], v[54:55], v[70:71]
	v_pk_add_f32 v[66:67], v[48:49], v[82:83]
	v_pk_add_f32 v[68:69], v[50:51], v[72:73]
	v_cvt_pk_bf16_f32 v48, v60, v61
	v_cvt_pk_bf16_f32 v49, v62, v63
	v_pk_mul_f32 v[50:51], v[60:61], v[60:61]
	v_pk_mul_f32 v[60:61], v[62:63], v[62:63]
	v_pk_mul_f32 v[62:63], v[56:57], v[56:57]
	v_pk_mul_f32 v[70:71], v[58:59], v[58:59]
	v_pk_mul_f32 v[72:73], v[52:53], v[52:53]
	v_pk_mul_f32 v[76:77], v[54:55], v[54:55]
	v_pk_mul_f32 v[78:79], v[66:67], v[66:67]
	v_pk_mul_f32 v[80:81], v[68:69], v[68:69]
	v_add_f32_e32 v78, v78, v79
	v_add_f32_e32 v80, v80, v81
	v_add_f32_e32 v76, v76, v77
	v_add_f32_e32 v72, v72, v73
	v_add_f32_e32 v70, v70, v71
	v_add_f32_e32 v62, v62, v63
	v_add_f32_e32 v60, v60, v61
	v_add_f32_e32 v50, v50, v51
	v_add_f32_e32 v51, v78, v80
	v_add_f32_e32 v61, v72, v76
	v_add_f32_e32 v62, v62, v70
	v_add_f32_e32 v50, v50, v60
	v_add_f32_e32 v51, v61, v51
	v_add_f32_e32 v50, v50, v62
	v_add_f32_e32 v60, v50, v51
	ds_bpermute_b32 v61, v159, v60
	v_cvt_pk_bf16_f32 v50, v56, v57
	v_cvt_pk_bf16_f32 v51, v58, v59
	global_store_dwordx4 v[74:75], v[48:51], off
	s_waitcnt lgkmcnt(0)
	s_nop 0
	v_add_f32_e32 v48, v60, v61
	ds_bpermute_b32 v49, v158, v48
	v_cvt_pk_bf16_f32 v50, v52, v53
	v_cvt_pk_bf16_f32 v51, v54, v55
	v_cvt_pk_bf16_f32 v52, v66, v67
	v_cvt_pk_bf16_f32 v53, v68, v69
	global_store_dwordx4 v[74:75], v[50:53], off offset:256
	s_and_saveexec_b64 s[30:31], s[4:5]
	s_cbranch_execz .LBB0_1161
	v_lshlrev_b64 v[50:51], 6, v[64:65]
	v_lshl_add_u64 v[50:51], s[14:15], 0, v[50:51]
	v_lshl_add_u64 v[50:51], s[28:29], 2, v[50:51]
	s_lshl_b32 s8, s46, 2
	v_lshl_add_u64 v[50:51], v[50:51], 0, s[8:9]
	s_waitcnt lgkmcnt(0)
	v_add_f32_e32 v48, v48, v49
	global_store_dword v[50:51], v48, off
.LBB0_1161:
	s_or_b64 exec, exec, s[30:31]
	v_add_u32_e32 v48, 0x90, v150
	s_waitcnt lgkmcnt(0)
	v_ashrrev_i32_e32 v49, 31, v48
	v_lshlrev_b64 v[50:51], 11, v[48:49]
	v_lshl_add_u64 v[50:51], s[12:13], 0, v[50:51]
	v_lshl_add_u64 v[58:59], v[148:149], 1, v[50:51]
	s_nop 1
	v_mov_b32_e32 v50, v216
	v_mov_b32_e32 v51, v217
	v_mov_b32_e32 v52, v218
	v_mov_b32_e32 v53, v219
	v_mov_b32_e32 v54, v220
	v_mov_b32_e32 v55, v221
	v_mov_b32_e32 v56, v222
	v_mov_b32_e32 v57, v223
	v_lshlrev_b32_e32 v60, 16, v50
	v_and_b32_e32 v61, 0xffff0000, v50
	v_lshlrev_b32_e32 v50, 16, v51
	v_and_b32_e32 v51, 0xffff0000, v51
	v_lshlrev_b32_e32 v62, 16, v52
	v_and_b32_e32 v63, 0xffff0000, v52
	v_lshlrev_b32_e32 v52, 16, v53
	v_and_b32_e32 v53, 0xffff0000, v53
	v_lshlrev_b32_e32 v64, 16, v54
	v_and_b32_e32 v65, 0xffff0000, v54
	v_lshlrev_b32_e32 v54, 16, v55
	v_and_b32_e32 v55, 0xffff0000, v55
	v_lshlrev_b32_e32 v66, 16, v56
	v_and_b32_e32 v67, 0xffff0000, v56
	v_lshlrev_b32_e32 v56, 16, v57
	v_and_b32_e32 v57, 0xffff0000, v57
	v_pk_add_f32 v[44:45], v[44:45], v[60:61]
	v_pk_add_f32 v[46:47], v[46:47], v[50:51]
	v_pk_add_f32 v[40:41], v[40:41], v[62:63]
	v_pk_add_f32 v[42:43], v[42:43], v[52:53]
	v_pk_add_f32 v[36:37], v[36:37], v[64:65]
	v_pk_add_f32 v[38:39], v[38:39], v[54:55]
	v_pk_add_f32 v[50:51], v[32:33], v[66:67]
	v_pk_add_f32 v[52:53], v[34:35], v[56:57]
	v_cvt_pk_bf16_f32 v32, v44, v45
	v_cvt_pk_bf16_f32 v33, v46, v47
	v_pk_mul_f32 v[34:35], v[44:45], v[44:45]
	v_pk_mul_f32 v[44:45], v[46:47], v[46:47]
	v_pk_mul_f32 v[46:47], v[40:41], v[40:41]
	v_pk_mul_f32 v[54:55], v[42:43], v[42:43]
	v_pk_mul_f32 v[56:57], v[36:37], v[36:37]
	v_pk_mul_f32 v[60:61], v[38:39], v[38:39]
	v_pk_mul_f32 v[62:63], v[50:51], v[50:51]
	v_pk_mul_f32 v[64:65], v[52:53], v[52:53]
	v_add_f32_e32 v62, v62, v63
	v_add_f32_e32 v64, v64, v65
	v_add_f32_e32 v60, v60, v61
	v_add_f32_e32 v56, v56, v57
	v_add_f32_e32 v54, v54, v55
	v_add_f32_e32 v46, v46, v47
	v_add_f32_e32 v44, v44, v45
	v_add_f32_e32 v34, v34, v35
	v_add_f32_e32 v35, v62, v64
	v_add_f32_e32 v45, v56, v60
	v_add_f32_e32 v46, v46, v54
	v_add_f32_e32 v34, v34, v44
	v_add_f32_e32 v35, v45, v35
	v_add_f32_e32 v34, v34, v46
	v_add_f32_e32 v44, v34, v35
	ds_bpermute_b32 v45, v159, v44
	v_cvt_pk_bf16_f32 v34, v40, v41
	v_cvt_pk_bf16_f32 v35, v42, v43
	global_store_dwordx4 v[58:59], v[32:35], off
	s_waitcnt lgkmcnt(0)
	s_nop 0
	v_add_f32_e32 v32, v44, v45
	ds_bpermute_b32 v33, v158, v32
	v_cvt_pk_bf16_f32 v34, v36, v37
	v_cvt_pk_bf16_f32 v35, v38, v39
	v_cvt_pk_bf16_f32 v36, v50, v51
	v_cvt_pk_bf16_f32 v37, v52, v53
	global_store_dwordx4 v[58:59], v[34:37], off offset:256
	s_and_saveexec_b64 s[30:31], s[4:5]
	s_cbranch_execz .LBB0_1163
	v_lshlrev_b64 v[34:35], 6, v[48:49]
	v_lshl_add_u64 v[34:35], s[14:15], 0, v[34:35]
	v_lshl_add_u64 v[34:35], s[28:29], 2, v[34:35]
	s_lshl_b32 s8, s46, 2
	v_lshl_add_u64 v[34:35], v[34:35], 0, s[8:9]
	s_waitcnt lgkmcnt(0)
	v_add_f32_e32 v32, v32, v33
	global_store_dword v[34:35], v32, off
.LBB0_1163:
	s_or_b64 exec, exec, s[30:31]
	v_add_u32_e32 v32, 0xa0, v150
	s_waitcnt lgkmcnt(0)
	v_ashrrev_i32_e32 v33, 31, v32
	v_lshlrev_b64 v[34:35], 11, v[32:33]
	v_lshl_add_u64 v[34:35], s[12:13], 0, v[34:35]
	v_lshl_add_u64 v[42:43], v[148:149], 1, v[34:35]
	s_nop 1
	v_mov_b32_e32 v34, v224
	v_mov_b32_e32 v35, v225
	v_mov_b32_e32 v36, v226
	v_mov_b32_e32 v37, v227
	v_mov_b32_e32 v38, v228
	v_mov_b32_e32 v39, v229
	v_mov_b32_e32 v40, v230
	v_mov_b32_e32 v41, v231
	v_lshlrev_b32_e32 v44, 16, v34
	v_and_b32_e32 v45, 0xffff0000, v34
	v_lshlrev_b32_e32 v34, 16, v35
	v_and_b32_e32 v35, 0xffff0000, v35
	v_lshlrev_b32_e32 v46, 16, v36
	v_and_b32_e32 v47, 0xffff0000, v36
	v_lshlrev_b32_e32 v36, 16, v37
	v_and_b32_e32 v37, 0xffff0000, v37
	v_lshlrev_b32_e32 v48, 16, v38
	v_and_b32_e32 v49, 0xffff0000, v38
	v_lshlrev_b32_e32 v38, 16, v39
	v_and_b32_e32 v39, 0xffff0000, v39
	v_lshlrev_b32_e32 v50, 16, v40
	v_and_b32_e32 v51, 0xffff0000, v40
	v_lshlrev_b32_e32 v40, 16, v41
	v_and_b32_e32 v41, 0xffff0000, v41
	v_pk_add_f32 v[28:29], v[28:29], v[44:45]
	v_pk_add_f32 v[30:31], v[30:31], v[34:35]
	v_pk_add_f32 v[24:25], v[24:25], v[46:47]
	v_pk_add_f32 v[26:27], v[26:27], v[36:37]
	v_pk_add_f32 v[20:21], v[20:21], v[48:49]
	v_pk_add_f32 v[22:23], v[22:23], v[38:39]
	v_pk_add_f32 v[34:35], v[16:17], v[50:51]
	v_pk_add_f32 v[36:37], v[18:19], v[40:41]
	v_cvt_pk_bf16_f32 v16, v28, v29
	v_cvt_pk_bf16_f32 v17, v30, v31
	v_pk_mul_f32 v[18:19], v[28:29], v[28:29]
	v_pk_mul_f32 v[28:29], v[30:31], v[30:31]
	v_pk_mul_f32 v[30:31], v[24:25], v[24:25]
	v_pk_mul_f32 v[38:39], v[26:27], v[26:27]
	v_pk_mul_f32 v[40:41], v[20:21], v[20:21]
	v_pk_mul_f32 v[44:45], v[22:23], v[22:23]
	v_pk_mul_f32 v[46:47], v[34:35], v[34:35]
	v_pk_mul_f32 v[48:49], v[36:37], v[36:37]
	v_add_f32_e32 v46, v46, v47
	v_add_f32_e32 v48, v48, v49
	v_add_f32_e32 v44, v44, v45
	v_add_f32_e32 v40, v40, v41
	v_add_f32_e32 v38, v38, v39
	v_add_f32_e32 v30, v30, v31
	v_add_f32_e32 v28, v28, v29
	v_add_f32_e32 v18, v18, v19
	v_add_f32_e32 v19, v46, v48
	v_add_f32_e32 v29, v40, v44
	v_add_f32_e32 v30, v30, v38
	v_add_f32_e32 v18, v18, v28
	v_add_f32_e32 v19, v29, v19
	v_add_f32_e32 v18, v18, v30
	v_add_f32_e32 v28, v18, v19
	ds_bpermute_b32 v29, v159, v28
	v_cvt_pk_bf16_f32 v18, v24, v25
	v_cvt_pk_bf16_f32 v19, v26, v27
	global_store_dwordx4 v[42:43], v[16:19], off
	s_waitcnt lgkmcnt(0)
	s_nop 0
	v_add_f32_e32 v16, v28, v29
	ds_bpermute_b32 v17, v158, v16
	v_cvt_pk_bf16_f32 v18, v20, v21
	v_cvt_pk_bf16_f32 v19, v22, v23
	v_cvt_pk_bf16_f32 v20, v34, v35
	v_cvt_pk_bf16_f32 v21, v36, v37
	global_store_dwordx4 v[42:43], v[18:21], off offset:256
	s_and_saveexec_b64 s[30:31], s[4:5]
	s_cbranch_execz .LBB0_1165
	v_lshlrev_b64 v[18:19], 6, v[32:33]
	v_lshl_add_u64 v[18:19], s[14:15], 0, v[18:19]
	v_lshl_add_u64 v[18:19], s[28:29], 2, v[18:19]
	s_lshl_b32 s8, s46, 2
	v_lshl_add_u64 v[18:19], v[18:19], 0, s[8:9]
	s_waitcnt lgkmcnt(0)
	v_add_f32_e32 v16, v16, v17
	global_store_dword v[18:19], v16, off
.LBB0_1165:
	s_or_b64 exec, exec, s[30:31]
	v_add_u32_e32 v16, 0xb0, v150
	s_waitcnt lgkmcnt(0)
	v_ashrrev_i32_e32 v17, 31, v16
	v_lshlrev_b64 v[18:19], 11, v[16:17]
	v_lshl_add_u64 v[18:19], s[12:13], 0, v[18:19]
	v_lshl_add_u64 v[26:27], v[148:149], 1, v[18:19]
	s_nop 1
	v_mov_b32_e32 v18, v238
	v_mov_b32_e32 v19, v239
	v_mov_b32_e32 v20, v240
	v_mov_b32_e32 v21, v241
	v_mov_b32_e32 v22, v242
	v_mov_b32_e32 v23, v243
	v_mov_b32_e32 v24, v244
	v_mov_b32_e32 v25, v245
	v_lshlrev_b32_e32 v28, 16, v18
	v_and_b32_e32 v29, 0xffff0000, v18
	v_lshlrev_b32_e32 v18, 16, v19
	v_and_b32_e32 v19, 0xffff0000, v19
	v_lshlrev_b32_e32 v30, 16, v20
	v_and_b32_e32 v31, 0xffff0000, v20
	v_lshlrev_b32_e32 v20, 16, v21
	v_and_b32_e32 v21, 0xffff0000, v21
	v_lshlrev_b32_e32 v32, 16, v22
	v_and_b32_e32 v33, 0xffff0000, v22
	v_lshlrev_b32_e32 v22, 16, v23
	v_and_b32_e32 v23, 0xffff0000, v23
	v_lshlrev_b32_e32 v34, 16, v24
	v_and_b32_e32 v35, 0xffff0000, v24
	v_lshlrev_b32_e32 v24, 16, v25
	v_and_b32_e32 v25, 0xffff0000, v25
	v_pk_add_f32 v[12:13], v[12:13], v[28:29]
	v_pk_add_f32 v[14:15], v[14:15], v[18:19]
	v_pk_add_f32 v[8:9], v[8:9], v[30:31]
	v_pk_add_f32 v[10:11], v[10:11], v[20:21]
	v_pk_add_f32 v[4:5], v[4:5], v[32:33]
	v_pk_add_f32 v[6:7], v[6:7], v[22:23]
	v_pk_add_f32 v[18:19], v[0:1], v[34:35]
	v_pk_add_f32 v[20:21], v[2:3], v[24:25]
	v_cvt_pk_bf16_f32 v0, v12, v13
	v_cvt_pk_bf16_f32 v1, v14, v15
	v_pk_mul_f32 v[2:3], v[12:13], v[12:13]
	v_pk_mul_f32 v[12:13], v[14:15], v[14:15]
	v_pk_mul_f32 v[14:15], v[8:9], v[8:9]
	v_pk_mul_f32 v[22:23], v[10:11], v[10:11]
	v_pk_mul_f32 v[24:25], v[4:5], v[4:5]
	v_pk_mul_f32 v[28:29], v[6:7], v[6:7]
	v_pk_mul_f32 v[30:31], v[18:19], v[18:19]
	v_pk_mul_f32 v[32:33], v[20:21], v[20:21]
	v_add_f32_e32 v30, v30, v31
	v_add_f32_e32 v32, v32, v33
	v_add_f32_e32 v28, v28, v29
	v_add_f32_e32 v24, v24, v25
	v_add_f32_e32 v22, v22, v23
	v_add_f32_e32 v14, v14, v15
	v_add_f32_e32 v12, v12, v13
	v_add_f32_e32 v2, v2, v3
	v_add_f32_e32 v3, v30, v32
	v_add_f32_e32 v13, v24, v28
	v_add_f32_e32 v14, v14, v22
	v_add_f32_e32 v2, v2, v12
	v_add_f32_e32 v3, v13, v3
	v_add_f32_e32 v2, v2, v14
	v_add_f32_e32 v12, v2, v3
	ds_bpermute_b32 v13, v159, v12
	v_cvt_pk_bf16_f32 v2, v8, v9
	v_cvt_pk_bf16_f32 v3, v10, v11
	global_store_dwordx4 v[26:27], v[0:3], off
	s_waitcnt lgkmcnt(0)
	s_nop 0
	v_add_f32_e32 v0, v12, v13
	ds_bpermute_b32 v1, v158, v0
	v_cvt_pk_bf16_f32 v2, v4, v5
	v_cvt_pk_bf16_f32 v3, v6, v7
	v_cvt_pk_bf16_f32 v4, v18, v19
	v_cvt_pk_bf16_f32 v5, v20, v21
	global_store_dwordx4 v[26:27], v[2:5], off offset:256
	s_and_saveexec_b64 s[30:31], s[4:5]
	s_cbranch_execz .LBB0_1167
	v_lshlrev_b64 v[2:3], 6, v[16:17]
	v_lshl_add_u64 v[2:3], s[14:15], 0, v[2:3]
	v_lshl_add_u64 v[2:3], s[28:29], 2, v[2:3]
	s_lshl_b32 s8, s46, 2
	v_lshl_add_u64 v[2:3], v[2:3], 0, s[8:9]
	s_waitcnt lgkmcnt(0)
	v_add_f32_e32 v0, v0, v1
	global_store_dword v[2:3], v0, off

.LBB0_1323:
	v_lshl_add_u32 v150, s53, 8, v131
	v_ashrrev_i32_e32 v151, 31, v150
	v_lshl_or_b32 v148, s10, 8, v152
	v_lshlrev_b64 v[158:159], 11, v[150:151]
	v_ashrrev_i32_e32 v149, 31, v148
	v_lshl_add_u64 v[158:159], s[14:15], 0, v[158:159]
	v_lshl_add_u64 v[168:169], v[148:149], 1, v[158:159]
	global_load_dwordx4 v[160:163], v[168:169], off
	global_load_dwordx4 v[164:167], v[168:169], off offset:256
	s_mov_b64 s[100:101], 0x8000
	v_lshl_add_u64 v[232:233], v[168:169], 0, s[100:101]
	global_load_dwordx4 v[184:187], v[232:233], off
	global_load_dwordx4 v[188:191], v[232:233], off offset:256
	s_mov_b64 s[100:101], 0x10000
	v_lshl_add_u64 v[232:233], v[168:169], 0, s[100:101]
	global_load_dwordx4 v[192:195], v[232:233], off
	global_load_dwordx4 v[196:199], v[232:233], off offset:256
	s_mov_b64 s[100:101], 0x18000
	v_lshl_add_u64 v[232:233], v[168:169], 0, s[100:101]
	global_load_dwordx4 v[200:203], v[232:233], off
	global_load_dwordx4 v[204:207], v[232:233], off offset:256
	s_mov_b64 s[100:101], 0x40000
	v_lshl_add_u64 v[232:233], v[168:169], 0, s[100:101]
	global_load_dwordx4 v[208:211], v[232:233], off
	global_load_dwordx4 v[212:215], v[232:233], off offset:256
	s_mov_b64 s[100:101], 0x48000
	v_lshl_add_u64 v[232:233], v[168:169], 0, s[100:101]
	global_load_dwordx4 v[216:219], v[232:233], off
	global_load_dwordx4 v[220:223], v[232:233], off offset:256
	s_mov_b64 s[100:101], 0x50000
	v_lshl_add_u64 v[232:233], v[168:169], 0, s[100:101]
	global_load_dwordx4 v[224:227], v[232:233], off
	global_load_dwordx4 v[228:231], v[232:233], off offset:256
	s_mov_b64 s[100:101], 0x58000
	v_lshl_add_u64 v[232:233], v[168:169], 0, s[100:101]
	global_load_dwordx4 v[238:241], v[232:233], off
	global_load_dwordx4 v[242:245], v[232:233], off offset:256
	v_and_b32_e32 v158, 64, v156
	v_xor_b32_e32 v157, 16, v156
	v_add_u32_e32 v158, 64, v158
	v_xor_b32_e32 v159, 32, v156
	v_cmp_lt_i32_e32 vcc, v157, v158
	s_lshl_b32 s24, s10, 2
	s_ashr_i32 s25, s24, 31
	v_cndmask_b32_e32 v157, v156, v157, vcc
	v_cmp_lt_i32_e32 vcc, v159, v158
	v_lshlrev_b32_e32 v158, 2, v157
	s_waitcnt vmcnt(0)
	v_lshlrev_b32_e32 v170, 16, v160
	v_and_b32_e32 v171, 0xffff0000, v160
	v_lshlrev_b32_e32 v160, 16, v161
	v_and_b32_e32 v161, 0xffff0000, v161
	v_lshlrev_b32_e32 v172, 16, v162
	v_and_b32_e32 v173, 0xffff0000, v162
	v_lshlrev_b32_e32 v162, 16, v163
	v_and_b32_e32 v163, 0xffff0000, v163
	v_lshlrev_b32_e32 v174, 16, v164
	v_and_b32_e32 v175, 0xffff0000, v164
	v_lshlrev_b32_e32 v164, 16, v165
	v_and_b32_e32 v165, 0xffff0000, v165
	v_lshlrev_b32_e32 v176, 16, v166
	v_and_b32_e32 v177, 0xffff0000, v166
	v_lshlrev_b32_e32 v166, 16, v167
	v_and_b32_e32 v167, 0xffff0000, v167
	v_pk_add_f32 v[124:125], v[124:125], v[170:171]
	v_pk_add_f32 v[126:127], v[126:127], v[160:161]
	v_pk_add_f32 v[120:121], v[120:121], v[172:173]
	v_pk_add_f32 v[122:123], v[122:123], v[162:163]
	v_pk_add_f32 v[116:117], v[116:117], v[174:175]
	v_pk_add_f32 v[118:119], v[118:119], v[164:165]
	v_pk_add_f32 v[160:161], v[112:113], v[176:177]
	v_pk_add_f32 v[162:163], v[114:115], v[166:167]
	v_cndmask_b32_e32 v159, v156, v159, vcc
	v_cvt_pk_bf16_f32 v112, v124, v125
	v_cvt_pk_bf16_f32 v113, v126, v127
	v_pk_mul_f32 v[114:115], v[124:125], v[124:125]
	v_pk_mul_f32 v[124:125], v[126:127], v[126:127]
	v_pk_mul_f32 v[126:127], v[120:121], v[120:121]
	v_pk_mul_f32 v[164:165], v[122:123], v[122:123]
	v_pk_mul_f32 v[166:167], v[116:117], v[116:117]
	v_pk_mul_f32 v[170:171], v[118:119], v[118:119]
	v_pk_mul_f32 v[172:173], v[160:161], v[160:161]
	v_pk_mul_f32 v[174:175], v[162:163], v[162:163]
	v_lshlrev_b32_e32 v157, 2, v159
	v_add_f32_e32 v159, v174, v175
	v_add_f32_e32 v172, v172, v173
	v_add_f32_e32 v170, v170, v171
	v_add_f32_e32 v166, v166, v167
	v_add_f32_e32 v164, v164, v165
	v_add_f32_e32 v126, v126, v127
	v_add_f32_e32 v124, v124, v125
	v_add_f32_e32 v114, v114, v115
	v_add_f32_e32 v115, v172, v159
	v_add_f32_e32 v125, v166, v170
	v_add_f32_e32 v126, v126, v164
	v_add_f32_e32 v114, v114, v124
	v_add_f32_e32 v115, v125, v115
	v_add_f32_e32 v114, v114, v126
	v_add_f32_e32 v124, v114, v115
	ds_bpermute_b32 v125, v158, v124
	v_cvt_pk_bf16_f32 v114, v120, v121
	v_cvt_pk_bf16_f32 v115, v122, v123
	global_store_dwordx4 v[168:169], v[112:115], off
	s_waitcnt lgkmcnt(0)
	s_nop 0
	v_add_f32_e32 v112, v124, v125
	ds_bpermute_b32 v113, v157, v112
	v_cvt_pk_bf16_f32 v114, v116, v117
	v_cvt_pk_bf16_f32 v115, v118, v119
	v_cvt_pk_bf16_f32 v116, v160, v161
	v_cvt_pk_bf16_f32 v117, v162, v163
	global_store_dwordx4 v[168:169], v[114:117], off offset:256
	s_and_saveexec_b64 s[26:27], s[4:5]
	s_cbranch_execz .LBB0_1325
	v_lshlrev_b64 v[114:115], 6, v[150:151]
	v_lshl_add_u64 v[114:115], s[16:17], 0, v[114:115]
	v_lshl_add_u64 v[114:115], s[24:25], 2, v[114:115]
	s_lshl_b32 s10, s40, 2
	v_lshl_add_u64 v[114:115], v[114:115], 0, s[10:11]
	s_waitcnt lgkmcnt(0)
	v_add_f32_e32 v112, v112, v113
	global_store_dword v[114:115], v112, off
.LBB0_1325:
	s_or_b64 exec, exec, s[26:27]
	v_or_b32_e32 v112, 16, v150
	s_waitcnt lgkmcnt(0)
	v_ashrrev_i32_e32 v113, 31, v112
	v_lshlrev_b64 v[114:115], 11, v[112:113]
	v_lshl_add_u64 v[114:115], s[14:15], 0, v[114:115]
	v_lshl_add_u64 v[122:123], v[148:149], 1, v[114:115]
	s_nop 1
	v_mov_b32_e32 v114, v184
	v_mov_b32_e32 v115, v185
	v_mov_b32_e32 v116, v186
	v_mov_b32_e32 v117, v187
	v_mov_b32_e32 v118, v188
	v_mov_b32_e32 v119, v189
	v_mov_b32_e32 v120, v190
	v_mov_b32_e32 v121, v191
	v_lshlrev_b32_e32 v124, 16, v114
	v_and_b32_e32 v125, 0xffff0000, v114
	v_lshlrev_b32_e32 v114, 16, v115
	v_and_b32_e32 v115, 0xffff0000, v115
	v_lshlrev_b32_e32 v126, 16, v116
	v_and_b32_e32 v127, 0xffff0000, v116
	v_lshlrev_b32_e32 v116, 16, v117
	v_and_b32_e32 v117, 0xffff0000, v117
	v_lshlrev_b32_e32 v160, 16, v118
	v_and_b32_e32 v161, 0xffff0000, v118
	v_lshlrev_b32_e32 v118, 16, v119
	v_and_b32_e32 v119, 0xffff0000, v119
	v_lshlrev_b32_e32 v162, 16, v120
	v_and_b32_e32 v163, 0xffff0000, v120
	v_lshlrev_b32_e32 v120, 16, v121
	v_and_b32_e32 v121, 0xffff0000, v121
	v_pk_add_f32 v[108:109], v[108:109], v[124:125]
	v_pk_add_f32 v[110:111], v[110:111], v[114:115]
	v_pk_add_f32 v[104:105], v[104:105], v[126:127]
	v_pk_add_f32 v[106:107], v[106:107], v[116:117]
	v_pk_add_f32 v[100:101], v[100:101], v[160:161]
	v_pk_add_f32 v[102:103], v[102:103], v[118:119]
	v_pk_add_f32 v[114:115], v[96:97], v[162:163]
	v_pk_add_f32 v[116:117], v[98:99], v[120:121]
	v_cvt_pk_bf16_f32 v96, v108, v109
	v_cvt_pk_bf16_f32 v97, v110, v111
	v_pk_mul_f32 v[98:99], v[108:109], v[108:109]
	v_pk_mul_f32 v[108:109], v[110:111], v[110:111]
	v_pk_mul_f32 v[110:111], v[104:105], v[104:105]
	v_pk_mul_f32 v[118:119], v[106:107], v[106:107]
	v_pk_mul_f32 v[120:121], v[100:101], v[100:101]
	v_pk_mul_f32 v[124:125], v[102:103], v[102:103]
	v_pk_mul_f32 v[126:127], v[114:115], v[114:115]
	v_pk_mul_f32 v[160:161], v[116:117], v[116:117]
	v_add_f32_e32 v126, v126, v127
	v_add_f32_e32 v151, v160, v161
	v_add_f32_e32 v124, v124, v125
	v_add_f32_e32 v120, v120, v121
	v_add_f32_e32 v118, v118, v119
	v_add_f32_e32 v110, v110, v111
	v_add_f32_e32 v108, v108, v109
	v_add_f32_e32 v98, v98, v99
	v_add_f32_e32 v99, v126, v151
	v_add_f32_e32 v109, v120, v124
	v_add_f32_e32 v110, v110, v118
	v_add_f32_e32 v98, v98, v108
	v_add_f32_e32 v99, v109, v99
	v_add_f32_e32 v98, v98, v110
	v_add_f32_e32 v108, v98, v99
	ds_bpermute_b32 v109, v158, v108
	v_cvt_pk_bf16_f32 v98, v104, v105
	v_cvt_pk_bf16_f32 v99, v106, v107
	global_store_dwordx4 v[122:123], v[96:99], off
	s_waitcnt lgkmcnt(0)
	s_nop 0
	v_add_f32_e32 v96, v108, v109
	ds_bpermute_b32 v97, v157, v96
	v_cvt_pk_bf16_f32 v98, v100, v101
	v_cvt_pk_bf16_f32 v99, v102, v103
	v_cvt_pk_bf16_f32 v100, v114, v115
	v_cvt_pk_bf16_f32 v101, v116, v117
	global_store_dwordx4 v[122:123], v[98:101], off offset:256
	s_and_saveexec_b64 s[26:27], s[4:5]
	s_cbranch_execz .LBB0_1327
	v_lshlrev_b64 v[98:99], 6, v[112:113]
	v_lshl_add_u64 v[98:99], s[16:17], 0, v[98:99]
	v_lshl_add_u64 v[98:99], s[24:25], 2, v[98:99]
	s_lshl_b32 s10, s40, 2
	v_lshl_add_u64 v[98:99], v[98:99], 0, s[10:11]
	s_waitcnt lgkmcnt(0)
	v_add_f32_e32 v96, v96, v97
	global_store_dword v[98:99], v96, off
.LBB0_1327:
	s_or_b64 exec, exec, s[26:27]
	v_or_b32_e32 v96, 32, v150
	s_waitcnt lgkmcnt(0)
	v_ashrrev_i32_e32 v97, 31, v96
	v_lshlrev_b64 v[98:99], 11, v[96:97]
	v_lshl_add_u64 v[98:99], s[14:15], 0, v[98:99]
	v_lshl_add_u64 v[106:107], v[148:149], 1, v[98:99]
	s_nop 1
	v_mov_b32_e32 v98, v192
	v_mov_b32_e32 v99, v193
	v_mov_b32_e32 v100, v194
	v_mov_b32_e32 v101, v195
	v_mov_b32_e32 v102, v196
	v_mov_b32_e32 v103, v197
	v_mov_b32_e32 v104, v198
	v_mov_b32_e32 v105, v199
	v_lshlrev_b32_e32 v108, 16, v98
	v_and_b32_e32 v109, 0xffff0000, v98
	v_lshlrev_b32_e32 v98, 16, v99
	v_and_b32_e32 v99, 0xffff0000, v99
	v_lshlrev_b32_e32 v110, 16, v100
	v_and_b32_e32 v111, 0xffff0000, v100
	v_lshlrev_b32_e32 v100, 16, v101
	v_and_b32_e32 v101, 0xffff0000, v101
	v_lshlrev_b32_e32 v112, 16, v102
	v_and_b32_e32 v113, 0xffff0000, v102
	v_lshlrev_b32_e32 v102, 16, v103
	v_and_b32_e32 v103, 0xffff0000, v103
	v_lshlrev_b32_e32 v114, 16, v104
	v_and_b32_e32 v115, 0xffff0000, v104
	v_lshlrev_b32_e32 v104, 16, v105
	v_and_b32_e32 v105, 0xffff0000, v105
	v_pk_add_f32 v[92:93], v[92:93], v[108:109]
	v_pk_add_f32 v[94:95], v[94:95], v[98:99]
	v_pk_add_f32 v[88:89], v[88:89], v[110:111]
	v_pk_add_f32 v[90:91], v[90:91], v[100:101]
	v_pk_add_f32 v[84:85], v[84:85], v[112:113]
	v_pk_add_f32 v[86:87], v[86:87], v[102:103]
	v_pk_add_f32 v[98:99], v[80:81], v[114:115]
	v_pk_add_f32 v[100:101], v[82:83], v[104:105]
	v_cvt_pk_bf16_f32 v80, v92, v93
	v_cvt_pk_bf16_f32 v81, v94, v95
	v_pk_mul_f32 v[82:83], v[92:93], v[92:93]
	v_pk_mul_f32 v[92:93], v[94:95], v[94:95]
	v_pk_mul_f32 v[94:95], v[88:89], v[88:89]
	v_pk_mul_f32 v[102:103], v[90:91], v[90:91]
	v_pk_mul_f32 v[104:105], v[84:85], v[84:85]
	v_pk_mul_f32 v[108:109], v[86:87], v[86:87]
	v_pk_mul_f32 v[110:111], v[98:99], v[98:99]
	v_pk_mul_f32 v[112:113], v[100:101], v[100:101]
	v_add_f32_e32 v110, v110, v111
	v_add_f32_e32 v112, v112, v113
	v_add_f32_e32 v108, v108, v109
	v_add_f32_e32 v104, v104, v105
	v_add_f32_e32 v102, v102, v103
	v_add_f32_e32 v94, v94, v95
	v_add_f32_e32 v92, v92, v93
	v_add_f32_e32 v82, v82, v83
	v_add_f32_e32 v83, v110, v112
	v_add_f32_e32 v93, v104, v108
	v_add_f32_e32 v94, v94, v102
	v_add_f32_e32 v82, v82, v92
	v_add_f32_e32 v83, v93, v83
	v_add_f32_e32 v82, v82, v94
	v_add_f32_e32 v92, v82, v83
	ds_bpermute_b32 v93, v158, v92
	v_cvt_pk_bf16_f32 v82, v88, v89
	v_cvt_pk_bf16_f32 v83, v90, v91
	global_store_dwordx4 v[106:107], v[80:83], off
	s_waitcnt lgkmcnt(0)
	s_nop 0
	v_add_f32_e32 v80, v92, v93
	ds_bpermute_b32 v81, v157, v80
	v_cvt_pk_bf16_f32 v82, v84, v85
	v_cvt_pk_bf16_f32 v83, v86, v87
	v_cvt_pk_bf16_f32 v84, v98, v99
	v_cvt_pk_bf16_f32 v85, v100, v101
	global_store_dwordx4 v[106:107], v[82:85], off offset:256
	s_and_saveexec_b64 s[26:27], s[4:5]
	s_cbranch_execz .LBB0_1329
	v_lshlrev_b64 v[82:83], 6, v[96:97]
	v_lshl_add_u64 v[82:83], s[16:17], 0, v[82:83]
	v_lshl_add_u64 v[82:83], s[24:25], 2, v[82:83]
	s_lshl_b32 s10, s40, 2
	v_lshl_add_u64 v[82:83], v[82:83], 0, s[10:11]
	s_waitcnt lgkmcnt(0)
	v_add_f32_e32 v80, v80, v81
	global_store_dword v[82:83], v80, off
.LBB0_1329:
	s_or_b64 exec, exec, s[26:27]
	v_or_b32_e32 v80, 48, v150
	s_waitcnt lgkmcnt(0)
	v_ashrrev_i32_e32 v81, 31, v80
	v_lshlrev_b64 v[82:83], 11, v[80:81]
	v_lshl_add_u64 v[82:83], s[14:15], 0, v[82:83]
	v_lshl_add_u64 v[90:91], v[148:149], 1, v[82:83]
	s_nop 1
	v_mov_b32_e32 v82, v200
	v_mov_b32_e32 v83, v201
	v_mov_b32_e32 v84, v202
	v_mov_b32_e32 v85, v203
	v_mov_b32_e32 v86, v204
	v_mov_b32_e32 v87, v205
	v_mov_b32_e32 v88, v206
	v_mov_b32_e32 v89, v207
	v_lshlrev_b32_e32 v92, 16, v82
	v_and_b32_e32 v93, 0xffff0000, v82
	v_lshlrev_b32_e32 v82, 16, v83
	v_and_b32_e32 v83, 0xffff0000, v83
	v_lshlrev_b32_e32 v94, 16, v84
	v_and_b32_e32 v95, 0xffff0000, v84
	v_lshlrev_b32_e32 v84, 16, v85
	v_and_b32_e32 v85, 0xffff0000, v85
	v_lshlrev_b32_e32 v96, 16, v86
	v_and_b32_e32 v97, 0xffff0000, v86
	v_lshlrev_b32_e32 v86, 16, v87
	v_and_b32_e32 v87, 0xffff0000, v87
	v_lshlrev_b32_e32 v98, 16, v88
	v_and_b32_e32 v99, 0xffff0000, v88
	v_lshlrev_b32_e32 v88, 16, v89
	v_and_b32_e32 v89, 0xffff0000, v89
	v_pk_add_f32 v[76:77], v[76:77], v[92:93]
	v_pk_add_f32 v[78:79], v[78:79], v[82:83]
	v_pk_add_f32 v[72:73], v[72:73], v[94:95]
	v_pk_add_f32 v[74:75], v[74:75], v[84:85]
	v_pk_add_f32 v[68:69], v[68:69], v[96:97]
	v_pk_add_f32 v[70:71], v[70:71], v[86:87]
	v_pk_add_f32 v[82:83], v[64:65], v[98:99]
	v_pk_add_f32 v[84:85], v[66:67], v[88:89]
	v_cvt_pk_bf16_f32 v64, v76, v77
	v_cvt_pk_bf16_f32 v65, v78, v79
	v_pk_mul_f32 v[66:67], v[76:77], v[76:77]
	v_pk_mul_f32 v[76:77], v[78:79], v[78:79]
	v_pk_mul_f32 v[78:79], v[72:73], v[72:73]
	v_pk_mul_f32 v[86:87], v[74:75], v[74:75]
	v_pk_mul_f32 v[88:89], v[68:69], v[68:69]
	v_pk_mul_f32 v[92:93], v[70:71], v[70:71]
	v_pk_mul_f32 v[94:95], v[82:83], v[82:83]
	v_pk_mul_f32 v[96:97], v[84:85], v[84:85]
	v_add_f32_e32 v94, v94, v95
	v_add_f32_e32 v96, v96, v97
	v_add_f32_e32 v92, v92, v93
	v_add_f32_e32 v88, v88, v89
	v_add_f32_e32 v86, v86, v87
	v_add_f32_e32 v78, v78, v79
	v_add_f32_e32 v76, v76, v77
	v_add_f32_e32 v66, v66, v67
	v_add_f32_e32 v67, v94, v96
	v_add_f32_e32 v77, v88, v92
	v_add_f32_e32 v78, v78, v86
	v_add_f32_e32 v66, v66, v76
	v_add_f32_e32 v67, v77, v67
	v_add_f32_e32 v66, v66, v78
	v_add_f32_e32 v76, v66, v67
	ds_bpermute_b32 v77, v158, v76
	v_cvt_pk_bf16_f32 v66, v72, v73
	v_cvt_pk_bf16_f32 v67, v74, v75
	global_store_dwordx4 v[90:91], v[64:67], off
	s_waitcnt lgkmcnt(0)
	s_nop 0
	v_add_f32_e32 v64, v76, v77
	ds_bpermute_b32 v65, v157, v64
	v_cvt_pk_bf16_f32 v66, v68, v69
	v_cvt_pk_bf16_f32 v67, v70, v71
	v_cvt_pk_bf16_f32 v68, v82, v83
	v_cvt_pk_bf16_f32 v69, v84, v85
	global_store_dwordx4 v[90:91], v[66:69], off offset:256
	s_and_saveexec_b64 s[26:27], s[4:5]
	s_cbranch_execz .LBB0_1331
	v_lshlrev_b64 v[66:67], 6, v[80:81]
	v_lshl_add_u64 v[66:67], s[16:17], 0, v[66:67]
	v_lshl_add_u64 v[66:67], s[24:25], 2, v[66:67]
	s_lshl_b32 s10, s40, 2
	v_lshl_add_u64 v[66:67], v[66:67], 0, s[10:11]
	s_waitcnt lgkmcnt(0)
	v_add_f32_e32 v64, v64, v65
	global_store_dword v[66:67], v64, off
.LBB0_1331:
	s_or_b64 exec, exec, s[26:27]
	v_add_u32_e32 v64, 0x80, v150
	s_waitcnt lgkmcnt(0)
	v_ashrrev_i32_e32 v65, 31, v64
	v_lshlrev_b64 v[66:67], 11, v[64:65]
	v_lshl_add_u64 v[66:67], s[14:15], 0, v[66:67]
	v_lshl_add_u64 v[74:75], v[148:149], 1, v[66:67]
	s_nop 1
	v_mov_b32_e32 v66, v208
	v_mov_b32_e32 v67, v209
	v_mov_b32_e32 v68, v210
	v_mov_b32_e32 v69, v211
	v_mov_b32_e32 v70, v212
	v_mov_b32_e32 v71, v213
	v_mov_b32_e32 v72, v214
	v_mov_b32_e32 v73, v215
	v_lshlrev_b32_e32 v76, 16, v66
	v_and_b32_e32 v77, 0xffff0000, v66
	v_lshlrev_b32_e32 v66, 16, v67
	v_and_b32_e32 v67, 0xffff0000, v67
	v_lshlrev_b32_e32 v78, 16, v68
	v_and_b32_e32 v79, 0xffff0000, v68
	v_lshlrev_b32_e32 v68, 16, v69
	v_and_b32_e32 v69, 0xffff0000, v69
	v_lshlrev_b32_e32 v80, 16, v70
	v_and_b32_e32 v81, 0xffff0000, v70
	v_lshlrev_b32_e32 v70, 16, v71
	v_and_b32_e32 v71, 0xffff0000, v71
	v_lshlrev_b32_e32 v82, 16, v72
	v_and_b32_e32 v83, 0xffff0000, v72
	v_lshlrev_b32_e32 v72, 16, v73
	v_and_b32_e32 v73, 0xffff0000, v73
	v_pk_add_f32 v[60:61], v[60:61], v[76:77]
	v_pk_add_f32 v[62:63], v[62:63], v[66:67]
	v_pk_add_f32 v[56:57], v[56:57], v[78:79]
	v_pk_add_f32 v[58:59], v[58:59], v[68:69]
	v_pk_add_f32 v[52:53], v[52:53], v[80:81]
	v_pk_add_f32 v[54:55], v[54:55], v[70:71]
	v_pk_add_f32 v[66:67], v[48:49], v[82:83]
	v_pk_add_f32 v[68:69], v[50:51], v[72:73]
	v_cvt_pk_bf16_f32 v48, v60, v61
	v_cvt_pk_bf16_f32 v49, v62, v63
	v_pk_mul_f32 v[50:51], v[60:61], v[60:61]
	v_pk_mul_f32 v[60:61], v[62:63], v[62:63]
	v_pk_mul_f32 v[62:63], v[56:57], v[56:57]
	v_pk_mul_f32 v[70:71], v[58:59], v[58:59]
	v_pk_mul_f32 v[72:73], v[52:53], v[52:53]
	v_pk_mul_f32 v[76:77], v[54:55], v[54:55]
	v_pk_mul_f32 v[78:79], v[66:67], v[66:67]
	v_pk_mul_f32 v[80:81], v[68:69], v[68:69]
	v_add_f32_e32 v78, v78, v79
	v_add_f32_e32 v80, v80, v81
	v_add_f32_e32 v76, v76, v77
	v_add_f32_e32 v72, v72, v73
	v_add_f32_e32 v70, v70, v71
	v_add_f32_e32 v62, v62, v63
	v_add_f32_e32 v60, v60, v61
	v_add_f32_e32 v50, v50, v51
	v_add_f32_e32 v51, v78, v80
	v_add_f32_e32 v61, v72, v76
	v_add_f32_e32 v62, v62, v70
	v_add_f32_e32 v50, v50, v60
	v_add_f32_e32 v51, v61, v51
	v_add_f32_e32 v50, v50, v62
	v_add_f32_e32 v60, v50, v51
	ds_bpermute_b32 v61, v158, v60
	v_cvt_pk_bf16_f32 v50, v56, v57
	v_cvt_pk_bf16_f32 v51, v58, v59
	global_store_dwordx4 v[74:75], v[48:51], off
	s_waitcnt lgkmcnt(0)
	s_nop 0
	v_add_f32_e32 v48, v60, v61
	ds_bpermute_b32 v49, v157, v48
	v_cvt_pk_bf16_f32 v50, v52, v53
	v_cvt_pk_bf16_f32 v51, v54, v55
	v_cvt_pk_bf16_f32 v52, v66, v67
	v_cvt_pk_bf16_f32 v53, v68, v69
	global_store_dwordx4 v[74:75], v[50:53], off offset:256
	s_and_saveexec_b64 s[26:27], s[4:5]
	s_cbranch_execz .LBB0_1333
	v_lshlrev_b64 v[50:51], 6, v[64:65]
	v_lshl_add_u64 v[50:51], s[16:17], 0, v[50:51]
	v_lshl_add_u64 v[50:51], s[24:25], 2, v[50:51]
	s_lshl_b32 s10, s40, 2
	v_lshl_add_u64 v[50:51], v[50:51], 0, s[10:11]
	s_waitcnt lgkmcnt(0)
	v_add_f32_e32 v48, v48, v49
	global_store_dword v[50:51], v48, off
.LBB0_1333:
	s_or_b64 exec, exec, s[26:27]
	v_add_u32_e32 v48, 0x90, v150
	s_waitcnt lgkmcnt(0)
	v_ashrrev_i32_e32 v49, 31, v48
	v_lshlrev_b64 v[50:51], 11, v[48:49]
	v_lshl_add_u64 v[50:51], s[14:15], 0, v[50:51]
	v_lshl_add_u64 v[58:59], v[148:149], 1, v[50:51]
	s_nop 1
	v_mov_b32_e32 v50, v216
	v_mov_b32_e32 v51, v217
	v_mov_b32_e32 v52, v218
	v_mov_b32_e32 v53, v219
	v_mov_b32_e32 v54, v220
	v_mov_b32_e32 v55, v221
	v_mov_b32_e32 v56, v222
	v_mov_b32_e32 v57, v223
	v_lshlrev_b32_e32 v60, 16, v50
	v_and_b32_e32 v61, 0xffff0000, v50
	v_lshlrev_b32_e32 v50, 16, v51
	v_and_b32_e32 v51, 0xffff0000, v51
	v_lshlrev_b32_e32 v62, 16, v52
	v_and_b32_e32 v63, 0xffff0000, v52
	v_lshlrev_b32_e32 v52, 16, v53
	v_and_b32_e32 v53, 0xffff0000, v53
	v_lshlrev_b32_e32 v64, 16, v54
	v_and_b32_e32 v65, 0xffff0000, v54
	v_lshlrev_b32_e32 v54, 16, v55
	v_and_b32_e32 v55, 0xffff0000, v55
	v_lshlrev_b32_e32 v66, 16, v56
	v_and_b32_e32 v67, 0xffff0000, v56
	v_lshlrev_b32_e32 v56, 16, v57
	v_and_b32_e32 v57, 0xffff0000, v57
	v_pk_add_f32 v[44:45], v[44:45], v[60:61]
	v_pk_add_f32 v[46:47], v[46:47], v[50:51]
	v_pk_add_f32 v[40:41], v[40:41], v[62:63]
	v_pk_add_f32 v[42:43], v[42:43], v[52:53]
	v_pk_add_f32 v[36:37], v[36:37], v[64:65]
	v_pk_add_f32 v[38:39], v[38:39], v[54:55]
	v_pk_add_f32 v[50:51], v[32:33], v[66:67]
	v_pk_add_f32 v[52:53], v[34:35], v[56:57]
	v_cvt_pk_bf16_f32 v32, v44, v45
	v_cvt_pk_bf16_f32 v33, v46, v47
	v_pk_mul_f32 v[34:35], v[44:45], v[44:45]
	v_pk_mul_f32 v[44:45], v[46:47], v[46:47]
	v_pk_mul_f32 v[46:47], v[40:41], v[40:41]
	v_pk_mul_f32 v[54:55], v[42:43], v[42:43]
	v_pk_mul_f32 v[56:57], v[36:37], v[36:37]
	v_pk_mul_f32 v[60:61], v[38:39], v[38:39]
	v_pk_mul_f32 v[62:63], v[50:51], v[50:51]
	v_pk_mul_f32 v[64:65], v[52:53], v[52:53]
	v_add_f32_e32 v62, v62, v63
	v_add_f32_e32 v64, v64, v65
	v_add_f32_e32 v60, v60, v61
	v_add_f32_e32 v56, v56, v57
	v_add_f32_e32 v54, v54, v55
	v_add_f32_e32 v46, v46, v47
	v_add_f32_e32 v44, v44, v45
	v_add_f32_e32 v34, v34, v35
	v_add_f32_e32 v35, v62, v64
	v_add_f32_e32 v45, v56, v60
	v_add_f32_e32 v46, v46, v54
	v_add_f32_e32 v34, v34, v44
	v_add_f32_e32 v35, v45, v35
	v_add_f32_e32 v34, v34, v46
	v_add_f32_e32 v44, v34, v35
	ds_bpermute_b32 v45, v158, v44
	v_cvt_pk_bf16_f32 v34, v40, v41
	v_cvt_pk_bf16_f32 v35, v42, v43
	global_store_dwordx4 v[58:59], v[32:35], off
	s_waitcnt lgkmcnt(0)
	s_nop 0
	v_add_f32_e32 v32, v44, v45
	ds_bpermute_b32 v33, v157, v32
	v_cvt_pk_bf16_f32 v34, v36, v37
	v_cvt_pk_bf16_f32 v35, v38, v39
	v_cvt_pk_bf16_f32 v36, v50, v51
	v_cvt_pk_bf16_f32 v37, v52, v53
	global_store_dwordx4 v[58:59], v[34:37], off offset:256
	s_and_saveexec_b64 s[26:27], s[4:5]
	s_cbranch_execz .LBB0_1335
	v_lshlrev_b64 v[34:35], 6, v[48:49]
	v_lshl_add_u64 v[34:35], s[16:17], 0, v[34:35]
	v_lshl_add_u64 v[34:35], s[24:25], 2, v[34:35]
	s_lshl_b32 s10, s40, 2
	v_lshl_add_u64 v[34:35], v[34:35], 0, s[10:11]
	s_waitcnt lgkmcnt(0)
	v_add_f32_e32 v32, v32, v33
	global_store_dword v[34:35], v32, off
.LBB0_1335:
	s_or_b64 exec, exec, s[26:27]
	v_add_u32_e32 v32, 0xa0, v150
	s_waitcnt lgkmcnt(0)
	v_ashrrev_i32_e32 v33, 31, v32
	v_lshlrev_b64 v[34:35], 11, v[32:33]
	v_lshl_add_u64 v[34:35], s[14:15], 0, v[34:35]
	v_lshl_add_u64 v[42:43], v[148:149], 1, v[34:35]
	s_nop 1
	v_mov_b32_e32 v34, v224
	v_mov_b32_e32 v35, v225
	v_mov_b32_e32 v36, v226
	v_mov_b32_e32 v37, v227
	v_mov_b32_e32 v38, v228
	v_mov_b32_e32 v39, v229
	v_mov_b32_e32 v40, v230
	v_mov_b32_e32 v41, v231
	v_lshlrev_b32_e32 v44, 16, v34
	v_and_b32_e32 v45, 0xffff0000, v34
	v_lshlrev_b32_e32 v34, 16, v35
	v_and_b32_e32 v35, 0xffff0000, v35
	v_lshlrev_b32_e32 v46, 16, v36
	v_and_b32_e32 v47, 0xffff0000, v36
	v_lshlrev_b32_e32 v36, 16, v37
	v_and_b32_e32 v37, 0xffff0000, v37
	v_lshlrev_b32_e32 v48, 16, v38
	v_and_b32_e32 v49, 0xffff0000, v38
	v_lshlrev_b32_e32 v38, 16, v39
	v_and_b32_e32 v39, 0xffff0000, v39
	v_lshlrev_b32_e32 v50, 16, v40
	v_and_b32_e32 v51, 0xffff0000, v40
	v_lshlrev_b32_e32 v40, 16, v41
	v_and_b32_e32 v41, 0xffff0000, v41
	v_pk_add_f32 v[28:29], v[28:29], v[44:45]
	v_pk_add_f32 v[30:31], v[30:31], v[34:35]
	v_pk_add_f32 v[24:25], v[24:25], v[46:47]
	v_pk_add_f32 v[26:27], v[26:27], v[36:37]
	v_pk_add_f32 v[20:21], v[20:21], v[48:49]
	v_pk_add_f32 v[22:23], v[22:23], v[38:39]
	v_pk_add_f32 v[34:35], v[16:17], v[50:51]
	v_pk_add_f32 v[36:37], v[18:19], v[40:41]
	v_cvt_pk_bf16_f32 v16, v28, v29
	v_cvt_pk_bf16_f32 v17, v30, v31
	v_pk_mul_f32 v[18:19], v[28:29], v[28:29]
	v_pk_mul_f32 v[28:29], v[30:31], v[30:31]
	v_pk_mul_f32 v[30:31], v[24:25], v[24:25]
	v_pk_mul_f32 v[38:39], v[26:27], v[26:27]
	v_pk_mul_f32 v[40:41], v[20:21], v[20:21]
	v_pk_mul_f32 v[44:45], v[22:23], v[22:23]
	v_pk_mul_f32 v[46:47], v[34:35], v[34:35]
	v_pk_mul_f32 v[48:49], v[36:37], v[36:37]
	v_add_f32_e32 v46, v46, v47
	v_add_f32_e32 v48, v48, v49
	v_add_f32_e32 v44, v44, v45
	v_add_f32_e32 v40, v40, v41
	v_add_f32_e32 v38, v38, v39
	v_add_f32_e32 v30, v30, v31
	v_add_f32_e32 v28, v28, v29
	v_add_f32_e32 v18, v18, v19
	v_add_f32_e32 v19, v46, v48
	v_add_f32_e32 v29, v40, v44
	v_add_f32_e32 v30, v30, v38
	v_add_f32_e32 v18, v18, v28
	v_add_f32_e32 v19, v29, v19
	v_add_f32_e32 v18, v18, v30
	v_add_f32_e32 v28, v18, v19
	ds_bpermute_b32 v29, v158, v28
	v_cvt_pk_bf16_f32 v18, v24, v25
	v_cvt_pk_bf16_f32 v19, v26, v27
	global_store_dwordx4 v[42:43], v[16:19], off
	s_waitcnt lgkmcnt(0)
	s_nop 0
	v_add_f32_e32 v16, v28, v29
	ds_bpermute_b32 v17, v157, v16
	v_cvt_pk_bf16_f32 v18, v20, v21
	v_cvt_pk_bf16_f32 v19, v22, v23
	v_cvt_pk_bf16_f32 v20, v34, v35
	v_cvt_pk_bf16_f32 v21, v36, v37
	global_store_dwordx4 v[42:43], v[18:21], off offset:256
	s_and_saveexec_b64 s[26:27], s[4:5]
	s_cbranch_execz .LBB0_1337
	v_lshlrev_b64 v[18:19], 6, v[32:33]
	v_lshl_add_u64 v[18:19], s[16:17], 0, v[18:19]
	v_lshl_add_u64 v[18:19], s[24:25], 2, v[18:19]
	s_lshl_b32 s10, s40, 2
	v_lshl_add_u64 v[18:19], v[18:19], 0, s[10:11]
	s_waitcnt lgkmcnt(0)
	v_add_f32_e32 v16, v16, v17
	global_store_dword v[18:19], v16, off
.LBB0_1337:
	s_or_b64 exec, exec, s[26:27]
	v_add_u32_e32 v16, 0xb0, v150
	s_waitcnt lgkmcnt(0)
	v_ashrrev_i32_e32 v17, 31, v16
	v_lshlrev_b64 v[18:19], 11, v[16:17]
	v_lshl_add_u64 v[18:19], s[14:15], 0, v[18:19]
	v_lshl_add_u64 v[26:27], v[148:149], 1, v[18:19]
	s_nop 1
	v_mov_b32_e32 v18, v238
	v_mov_b32_e32 v19, v239
	v_mov_b32_e32 v20, v240
	v_mov_b32_e32 v21, v241
	v_mov_b32_e32 v22, v242
	v_mov_b32_e32 v23, v243
	v_mov_b32_e32 v24, v244
	v_mov_b32_e32 v25, v245
	v_lshlrev_b32_e32 v28, 16, v18
	v_and_b32_e32 v29, 0xffff0000, v18
	v_lshlrev_b32_e32 v18, 16, v19
	v_and_b32_e32 v19, 0xffff0000, v19
	v_lshlrev_b32_e32 v30, 16, v20
	v_and_b32_e32 v31, 0xffff0000, v20
	v_lshlrev_b32_e32 v20, 16, v21
	v_and_b32_e32 v21, 0xffff0000, v21
	v_lshlrev_b32_e32 v32, 16, v22
	v_and_b32_e32 v33, 0xffff0000, v22
	v_lshlrev_b32_e32 v22, 16, v23
	v_and_b32_e32 v23, 0xffff0000, v23
	v_lshlrev_b32_e32 v34, 16, v24
	v_and_b32_e32 v35, 0xffff0000, v24
	v_lshlrev_b32_e32 v24, 16, v25
	v_and_b32_e32 v25, 0xffff0000, v25
	v_pk_add_f32 v[12:13], v[12:13], v[28:29]
	v_pk_add_f32 v[14:15], v[14:15], v[18:19]
	v_pk_add_f32 v[8:9], v[8:9], v[30:31]
	v_pk_add_f32 v[10:11], v[10:11], v[20:21]
	v_pk_add_f32 v[4:5], v[4:5], v[32:33]
	v_pk_add_f32 v[6:7], v[6:7], v[22:23]
	v_pk_add_f32 v[18:19], v[0:1], v[34:35]
	v_pk_add_f32 v[20:21], v[2:3], v[24:25]
	v_cvt_pk_bf16_f32 v0, v12, v13
	v_cvt_pk_bf16_f32 v1, v14, v15
	v_pk_mul_f32 v[2:3], v[12:13], v[12:13]
	v_pk_mul_f32 v[12:13], v[14:15], v[14:15]
	v_pk_mul_f32 v[14:15], v[8:9], v[8:9]
	v_pk_mul_f32 v[22:23], v[10:11], v[10:11]
	v_pk_mul_f32 v[24:25], v[4:5], v[4:5]
	v_pk_mul_f32 v[28:29], v[6:7], v[6:7]
	v_pk_mul_f32 v[30:31], v[18:19], v[18:19]
	v_pk_mul_f32 v[32:33], v[20:21], v[20:21]
	v_add_f32_e32 v30, v30, v31
	v_add_f32_e32 v32, v32, v33
	v_add_f32_e32 v28, v28, v29
	v_add_f32_e32 v24, v24, v25
	v_add_f32_e32 v22, v22, v23
	v_add_f32_e32 v14, v14, v15
	v_add_f32_e32 v12, v12, v13
	v_add_f32_e32 v2, v2, v3
	v_add_f32_e32 v3, v30, v32
	v_add_f32_e32 v13, v24, v28
	v_add_f32_e32 v14, v14, v22
	v_add_f32_e32 v2, v2, v12
	v_add_f32_e32 v3, v13, v3
	v_add_f32_e32 v2, v2, v14
	v_add_f32_e32 v12, v2, v3
	ds_bpermute_b32 v13, v158, v12
	v_cvt_pk_bf16_f32 v2, v8, v9
	v_cvt_pk_bf16_f32 v3, v10, v11
	global_store_dwordx4 v[26:27], v[0:3], off
	s_waitcnt lgkmcnt(0)
	s_nop 0
	v_add_f32_e32 v0, v12, v13
	ds_bpermute_b32 v1, v157, v0
	v_cvt_pk_bf16_f32 v2, v4, v5
	v_cvt_pk_bf16_f32 v3, v6, v7
	v_cvt_pk_bf16_f32 v4, v18, v19
	v_cvt_pk_bf16_f32 v5, v20, v21
	global_store_dwordx4 v[26:27], v[2:5], off offset:256
	s_and_saveexec_b64 s[26:27], s[4:5]
	s_cbranch_execz .LBB0_1339
	v_lshlrev_b64 v[2:3], 6, v[16:17]
	v_lshl_add_u64 v[2:3], s[16:17], 0, v[2:3]
	v_lshl_add_u64 v[2:3], s[24:25], 2, v[2:3]
	s_lshl_b32 s10, s40, 2
	v_lshl_add_u64 v[2:3], v[2:3], 0, s[10:11]
	s_waitcnt lgkmcnt(0)
	v_add_f32_e32 v0, v0, v1
	global_store_dword v[2:3], v0, off

	.amdhsa_kernel _Z4mega4Args
		.amdhsa_group_segment_fixed_size 0
		.amdhsa_private_segment_fixed_size 0
		.amdhsa_kernarg_size 432
		.amdhsa_user_sgpr_count 2
		.amdhsa_user_sgpr_dispatch_ptr 0
		.amdhsa_user_sgpr_queue_ptr 0
		.amdhsa_user_sgpr_kernarg_segment_ptr 1
		.amdhsa_user_sgpr_dispatch_id 0
		.amdhsa_user_sgpr_kernarg_preload_length 0
		.amdhsa_user_sgpr_kernarg_preload_offset 0
		.amdhsa_user_sgpr_private_segment_size 0
		.amdhsa_uses_dynamic_stack 0
		.amdhsa_enable_private_segment 0
		.amdhsa_system_sgpr_workgroup_id_x 1
		.amdhsa_system_sgpr_workgroup_id_y 0
		.amdhsa_system_sgpr_workgroup_id_z 0
		.amdhsa_system_sgpr_workgroup_info 0
		.amdhsa_system_vgpr_workitem_id 2
		.amdhsa_next_free_vgpr 256
		.amdhsa_next_free_sgpr 102
		.amdhsa_accum_offset 256
		.amdhsa_reserve_vcc 1
		.amdhsa_float_round_mode_32 0
		.amdhsa_float_round_mode_16_64 0
		.amdhsa_float_denorm_mode_32 3
		.amdhsa_float_denorm_mode_16_64 3
		.amdhsa_dx10_clamp 1
		.amdhsa_ieee_mode 1
		.amdhsa_fp16_overflow 0
		.amdhsa_tg_split 0
		.amdhsa_exception_fp_ieee_invalid_op 0
		.amdhsa_exception_fp_denorm_src 0
		.amdhsa_exception_fp_ieee_div_zero 0
		.amdhsa_exception_fp_ieee_overflow 0
		.amdhsa_exception_fp_ieee_underflow 0
		.amdhsa_exception_fp_ieee_inexact 0
		.amdhsa_exception_int_div_zero 0
	.end_amdhsa_kernel

amdhsa.kernels:
  - .agpr_count:     0
    .args:
      - .offset:         0
        .size:           176
        .value_kind:     by_value
      - .offset:         176
        .size:           4
        .value_kind:     hidden_block_count_x
      - .offset:         180
        .size:           4
        .value_kind:     hidden_block_count_y
      - .offset:         184
        .size:           4
        .value_kind:     hidden_block_count_z
      - .offset:         188
        .size:           2
        .value_kind:     hidden_group_size_x
      - .offset:         190
        .size:           2
        .value_kind:     hidden_group_size_y
      - .offset:         192
        .size:           2
        .value_kind:     hidden_group_size_z
      - .offset:         194
        .size:           2
        .value_kind:     hidden_remainder_x
      - .offset:         196
        .size:           2
        .value_kind:     hidden_remainder_y
      - .offset:         198
        .size:           2
        .value_kind:     hidden_remainder_z
      - .offset:         216
        .size:           8
        .value_kind:     hidden_global_offset_x
      - .offset:         224
        .size:           8
        .value_kind:     hidden_global_offset_y
      - .offset:         232
        .size:           8
        .value_kind:     hidden_global_offset_z
      - .offset:         240
        .size:           2
        .value_kind:     hidden_grid_dims
      - .offset:         264
        .size:           8
        .value_kind:     hidden_multigrid_sync_arg
      - .offset:         296
        .size:           4
        .value_kind:     hidden_dynamic_lds_size
    .group_segment_fixed_size: 0
    .kernarg_segment_align: 8
    .kernarg_segment_size: 432
    .language:       OpenCL C
    .language_version:
      - 2
      - 0
    .max_flat_workgroup_size: 512
    .name:           _Z4mega4Args
    .private_segment_fixed_size: 0
    .sgpr_count:     108
    .sgpr_spill_count: 11
    .symbol:         _Z4mega4Args.kd
    .uniform_work_group_size: 1
    .uses_dynamic_stack: false
    .vgpr_count:     256
    .vgpr_spill_count: 0
    .wavefront_size: 64
